# helper weight conversion rewritten by hand: LDS transpose tile pitch 65 floats (bank-conflict-free column reads), scalar address arithmetic, continuous 2-set load pipeline with queue grabs of 4; same
# baseline (speedup 1.0000x reference)
.LBB0_379:
	s_andn2_b64 vcc, exec, s[0:1]
	s_cbranch_vccnz .LBB0_767
	v_readlane_b32 s1, v255, 1
	s_nop 3
	s_cmpk_eq_i32 s1, 0xe0
	s_cselect_b32 s1, 0xf0, s1
	v_readlane_b32 s0, v253, 49
	s_nop 3
	s_cmp_eq_u32 s0, 3
	v_readlane_b32 s0, v252, 0
	s_nop 3
	s_cselect_b32 s58, s0, s1
	v_readlane_b32 s0, v253, 9
	v_readlane_b32 s1, v253, 10
	s_cmp_ge_i32 s0, s58
	s_mov_b64 s[0:1], -1
	s_cbranch_scc0 .LBB0_434
	v_readlane_b32 s0, v253, 49
	v_readlane_b32 s6, v252, 1
	v_readlane_b32 s7, v252, 2
	s_nop 3
	s_add_i32 s4, s0, 1
	s_add_u32 s6, s6, 0xffffff58
	s_addc_u32 s7, s7, -1
	s_load_dwordx2 s[40:41], s[6:7], 0x58
	s_load_dwordx2 s[42:43], s[6:7], 0x70
	s_load_dwordx4 s[44:47], s[6:7], 0x78
	v_and_b32_e32 v2, 63, v0
	v_lshrrev_b32_e32 v3, 4, v2
	v_and_b32_e32 v4, 15, v2
	v_lshlrev_b32_e32 v4, 4, v4
	v_lshrrev_b32_e32 v5, 3, v2
	v_and_b32_e32 v6, 7, v2
	v_lshlrev_b32_e32 v6, 4, v6
	v_readfirstlane_b32 s0, v0
	s_nop 3
	s_lshr_b32 s0, s0, 6
	s_mulk_i32 s0, 0x4400
	v_mul_u32_u24_e32 v7, 0x104, v3
	v_add3_u32 v7, v7, v4, s0
	v_mul_u32_u24_e32 v8, 0x82, v6
	v_lshl_add_u32 v8, v5, 2, v8
	v_add_u32_e32 v8, s0, v8
	v_add_u32_e32 v9, 0x410, v8
	v_mov_b32_e32 v18, 0
	v_mov_b32_e32 v20, 4
	s_waitcnt lgkmcnt(0)
	s_lshl_b32 s0, s4, 26
	s_lshl_b32 s1, s4, 24
	s_add_u32 s40, s40, s0
	s_addc_u32 s41, s41, 0
	s_add_u32 s42, s42, s1
	s_addc_u32 s43, s43, 0
	s_add_u32 s44, s44, s0
	s_addc_u32 s45, s45, 0
	s_add_u32 s46, s46, s0
	s_addc_u32 s47, s47, 0
	s_lshl_b32 s0, s4, 25
	s_lshl_b32 s1, s4, 23
	s_add_u32 s48, s26, 0x200000
	s_addc_u32 s49, s27, 0
	s_add_u32 s48, s48, s0
	s_addc_u32 s49, s49, 0
	s_add_u32 s50, s26, 0x8200000
	s_addc_u32 s51, s27, 0
	s_add_u32 s50, s50, s1
	s_addc_u32 s51, s51, 0
	s_add_u32 s52, s26, 0xa200000
	s_addc_u32 s53, s27, 0
	s_add_u32 s52, s52, s0
	s_addc_u32 s53, s53, 0
	s_add_u32 s54, s26, 0x12200000
	s_addc_u32 s55, s27, 0
	s_add_u32 s54, s54, s0
	s_addc_u32 s55, s55, 0
	s_lshl_b32 s0, s4, 8
	s_add_u32 s56, s26, s0
	s_addc_u32 s57, s27, 0
	v_cmp_eq_u32_e32 vcc, 0, v2
	s_and_saveexec_b64 s[0:1], vcc
	global_atomic_add v19, v18, v20, s[56:57] offset:512 sc0
	s_or_b64 exec, exec, s[0:1]
	s_waitcnt vmcnt(0)
	v_readfirstlane_b32 s60, v19
	s_nop 3
	s_cmpk_lt_u32 s60, 0x1400
	s_cbranch_scc0 .Lcvi_done
	s_mov_b32 s61, 1
.Lcvi_grab:
	v_cmp_eq_u32_e32 vcc, 0, v2
	s_and_saveexec_b64 s[0:1], vcc
	global_atomic_add v19, v18, v20, s[56:57] offset:512 sc0
	s_or_b64 exec, exec, s[0:1]
	s_add_i32 s13, s60, 0x0
	s_cmpk_lt_u32 s13, 0x1000
	s_cbranch_scc1 .Lcvi_dA0_c0
	s_cmpk_lt_u32 s13, 0x1400
	s_cbranch_scc1 .Lcvi_dA0_c1
	s_cmpk_lt_u32 s13, 0x2400
	s_cbranch_scc1 .Lcvi_dA0_c2
	s_add_i32 s13, s13, 0xffffdc00
	s_mov_b64 s[16:17], s[46:47]
	s_mov_b64 s[62:63], s[54:55]
	s_mov_b32 s14, 5
	s_mov_b32 s15, 19
	s_mov_b32 s19, 20
	s_mov_b32 s1, 13
	s_mov_b32 s8, 14
	s_branch .Lcvi_dA0_go
.Lcvi_dA0_c0:
	s_mov_b64 s[16:17], s[40:41]
	s_mov_b64 s[62:63], s[48:49]
	s_mov_b32 s14, 7
	s_mov_b32 s15, 21
	s_mov_b32 s19, 18
	s_mov_b32 s1, 15
	s_mov_b32 s8, 12
	s_branch .Lcvi_dA0_go
.Lcvi_dA0_c1:
	s_add_i32 s13, s13, 0xfffff000
	s_mov_b64 s[16:17], s[42:43]
	s_mov_b64 s[62:63], s[50:51]
	s_mov_b32 s14, 5
	s_mov_b32 s15, 19
	s_mov_b32 s19, 18
	s_mov_b32 s1, 13
	s_mov_b32 s8, 12
	s_branch .Lcvi_dA0_go
.Lcvi_dA0_c2:
	s_add_i32 s13, s13, 0xffffec00
	s_mov_b64 s[16:17], s[44:45]
	s_mov_b64 s[62:63], s[52:53]
	s_mov_b32 s14, 7
	s_mov_b32 s15, 21
	s_mov_b32 s19, 18
	s_mov_b32 s1, 15
	s_mov_b32 s8, 12
.Lcvi_dA0_go:
	s_lshr_b32 s0, s13, s14
	s_lshl_b32 s18, s0, s14
	s_sub_i32 s13, s13, s18
	s_lshl_b32 s18, s0, s15
	s_lshl_b32 s14, s13, 8
	s_add_i32 s18, s18, s14
	s_add_u32 s16, s16, s18
	s_addc_u32 s17, s17, 0
	s_lshl_b32 s18, s13, s19
	s_lshl_b32 s14, s0, 7
	s_add_i32 s18, s18, s14
	s_add_u32 s6, s62, s18
	s_addc_u32 s7, s63, 0
	s_add_i32 s18, s1, 2
	s_lshl_b32 s18, 1, s18
	v_lshlrev_b32_e32 v16, s1, v3
	v_or_b32_e32 v16, v16, v4
	global_load_dwordx4 v[72:75], v16, s[16:17] nt
	s_add_u32 s16, s16, s18
	s_addc_u32 s17, s17, 0
	global_load_dwordx4 v[76:79], v16, s[16:17] nt
	s_add_u32 s16, s16, s18
	s_addc_u32 s17, s17, 0
	global_load_dwordx4 v[80:83], v16, s[16:17] nt
	s_add_u32 s16, s16, s18
	s_addc_u32 s17, s17, 0
	global_load_dwordx4 v[84:87], v16, s[16:17] nt
	s_add_u32 s16, s16, s18
	s_addc_u32 s17, s17, 0
	global_load_dwordx4 v[88:91], v16, s[16:17] nt
	s_add_u32 s16, s16, s18
	s_addc_u32 s17, s17, 0
	global_load_dwordx4 v[92:95], v16, s[16:17] nt
	s_add_u32 s16, s16, s18
	s_addc_u32 s17, s17, 0
	global_load_dwordx4 v[96:99], v16, s[16:17] nt
	s_add_u32 s16, s16, s18
	s_addc_u32 s17, s17, 0
	global_load_dwordx4 v[100:103], v16, s[16:17] nt
	s_add_u32 s16, s16, s18
	s_addc_u32 s17, s17, 0
	global_load_dwordx4 v[104:107], v16, s[16:17] nt
	s_add_u32 s16, s16, s18
	s_addc_u32 s17, s17, 0
	global_load_dwordx4 v[108:111], v16, s[16:17] nt
	s_add_u32 s16, s16, s18
	s_addc_u32 s17, s17, 0
	global_load_dwordx4 v[112:115], v16, s[16:17] nt
	s_add_u32 s16, s16, s18
	s_addc_u32 s17, s17, 0
	global_load_dwordx4 v[116:119], v16, s[16:17] nt
	s_add_u32 s16, s16, s18
	s_addc_u32 s17, s17, 0
	global_load_dwordx4 v[120:123], v16, s[16:17] nt
	s_add_u32 s16, s16, s18
	s_addc_u32 s17, s17, 0
	global_load_dwordx4 v[124:127], v16, s[16:17] nt
	s_add_u32 s16, s16, s18
	s_addc_u32 s17, s17, 0
	global_load_dwordx4 v[128:131], v16, s[16:17] nt
	s_add_u32 s16, s16, s18
	s_addc_u32 s17, s17, 0
	global_load_dwordx4 v[132:135], v16, s[16:17] nt
	s_cmp_eq_u32 s61, 1
	s_cbranch_scc1 .Lcvi_first
	s_waitcnt vmcnt(25)
	ds_write_b32 v7, v136 offset:0
	ds_write_b32 v7, v137 offset:4
	ds_write_b32 v7, v138 offset:8
	ds_write_b32 v7, v139 offset:12
	ds_write_b32 v7, v140 offset:1040
	ds_write_b32 v7, v141 offset:1044
	ds_write_b32 v7, v142 offset:1048
	ds_write_b32 v7, v143 offset:1052
	ds_write_b32 v7, v144 offset:2080
	ds_write_b32 v7, v145 offset:2084
	ds_write_b32 v7, v146 offset:2088
	ds_write_b32 v7, v147 offset:2092
	ds_write_b32 v7, v148 offset:3120
	ds_write_b32 v7, v149 offset:3124
	ds_write_b32 v7, v150 offset:3128
	ds_write_b32 v7, v151 offset:3132
	ds_write_b32 v7, v152 offset:4160
	ds_write_b32 v7, v153 offset:4164
	ds_write_b32 v7, v154 offset:4168
	ds_write_b32 v7, v155 offset:4172
	ds_write_b32 v7, v156 offset:5200
	ds_write_b32 v7, v157 offset:5204
	ds_write_b32 v7, v158 offset:5208
	ds_write_b32 v7, v159 offset:5212
	ds_write_b32 v7, v160 offset:6240
	ds_write_b32 v7, v161 offset:6244
	ds_write_b32 v7, v162 offset:6248
	ds_write_b32 v7, v163 offset:6252
	ds_write_b32 v7, v164 offset:7280
	ds_write_b32 v7, v165 offset:7284
	ds_write_b32 v7, v166 offset:7288
	ds_write_b32 v7, v167 offset:7292
	ds_write_b32 v7, v168 offset:8320
	ds_write_b32 v7, v169 offset:8324
	ds_write_b32 v7, v170 offset:8328
	ds_write_b32 v7, v171 offset:8332
	ds_write_b32 v7, v172 offset:9360
	ds_write_b32 v7, v173 offset:9364
	ds_write_b32 v7, v174 offset:9368
	ds_write_b32 v7, v175 offset:9372
	ds_write_b32 v7, v176 offset:10400
	ds_write_b32 v7, v177 offset:10404
	ds_write_b32 v7, v178 offset:10408
	ds_write_b32 v7, v179 offset:10412
	ds_write_b32 v7, v180 offset:11440
	ds_write_b32 v7, v181 offset:11444
	ds_write_b32 v7, v182 offset:11448
	ds_write_b32 v7, v183 offset:11452
	ds_write_b32 v7, v184 offset:12480
	ds_write_b32 v7, v185 offset:12484
	ds_write_b32 v7, v186 offset:12488
	ds_write_b32 v7, v187 offset:12492
	ds_write_b32 v7, v188 offset:13520
	ds_write_b32 v7, v189 offset:13524
	ds_write_b32 v7, v190 offset:13528
	ds_write_b32 v7, v191 offset:13532
	ds_write_b32 v7, v192 offset:14560
	ds_write_b32 v7, v193 offset:14564
	ds_write_b32 v7, v194 offset:14568
	ds_write_b32 v7, v195 offset:14572
	ds_write_b32 v7, v196 offset:15600
	ds_write_b32 v7, v197 offset:15604
	ds_write_b32 v7, v198 offset:15608
	ds_write_b32 v7, v199 offset:15612
	v_lshlrev_b32_e32 v17, s12, v5
	v_or_b32_e32 v17, v17, v6
	s_lshl_b32 s13, 8, s12
	s_mov_b32 s14, s10
	s_mov_b32 s15, s11
	ds_read2_b32 v[36:37], v8 offset0:0 offset1:65
	ds_read2_b32 v[38:39], v8 offset0:130 offset1:195
	ds_read2_b32 v[40:41], v9 offset0:0 offset1:65
	ds_read2_b32 v[42:43], v9 offset0:130 offset1:195
	ds_read2_b32 v[44:45], v8 offset0:8 offset1:73
	ds_read2_b32 v[46:47], v8 offset0:138 offset1:203
	ds_read2_b32 v[48:49], v9 offset0:8 offset1:73
	ds_read2_b32 v[50:51], v9 offset0:138 offset1:203
	s_waitcnt lgkmcnt(4)
	v_cvt_pk_bf16_f32 v52, v36, v37
	v_cvt_pk_bf16_f32 v53, v38, v39
	v_cvt_pk_bf16_f32 v54, v40, v41
	v_cvt_pk_bf16_f32 v55, v42, v43
	global_store_dwordx4 v17, v[52:55], s[14:15] nt
	s_add_u32 s14, s14, s13
	s_addc_u32 s15, s15, 0
	ds_read2_b32 v[36:37], v8 offset0:16 offset1:81
	ds_read2_b32 v[38:39], v8 offset0:146 offset1:211
	ds_read2_b32 v[40:41], v9 offset0:16 offset1:81
	ds_read2_b32 v[42:43], v9 offset0:146 offset1:211
	s_waitcnt lgkmcnt(4)
	v_cvt_pk_bf16_f32 v56, v44, v45
	v_cvt_pk_bf16_f32 v57, v46, v47
	v_cvt_pk_bf16_f32 v58, v48, v49
	v_cvt_pk_bf16_f32 v59, v50, v51
	global_store_dwordx4 v17, v[56:59], s[14:15] nt
	s_add_u32 s14, s14, s13
	s_addc_u32 s15, s15, 0
	ds_read2_b32 v[44:45], v8 offset0:24 offset1:89
	ds_read2_b32 v[46:47], v8 offset0:154 offset1:219
	ds_read2_b32 v[48:49], v9 offset0:24 offset1:89
	ds_read2_b32 v[50:51], v9 offset0:154 offset1:219
	s_waitcnt lgkmcnt(4)
	v_cvt_pk_bf16_f32 v52, v36, v37
	v_cvt_pk_bf16_f32 v53, v38, v39
	v_cvt_pk_bf16_f32 v54, v40, v41
	v_cvt_pk_bf16_f32 v55, v42, v43
	global_store_dwordx4 v17, v[52:55], s[14:15] nt
	s_add_u32 s14, s14, s13
	s_addc_u32 s15, s15, 0
	ds_read2_b32 v[36:37], v8 offset0:32 offset1:97
	ds_read2_b32 v[38:39], v8 offset0:162 offset1:227
	ds_read2_b32 v[40:41], v9 offset0:32 offset1:97
	ds_read2_b32 v[42:43], v9 offset0:162 offset1:227
	s_waitcnt lgkmcnt(4)
	v_cvt_pk_bf16_f32 v56, v44, v45
	v_cvt_pk_bf16_f32 v57, v46, v47
	v_cvt_pk_bf16_f32 v58, v48, v49
	v_cvt_pk_bf16_f32 v59, v50, v51
	global_store_dwordx4 v17, v[56:59], s[14:15] nt
	s_add_u32 s14, s14, s13
	s_addc_u32 s15, s15, 0
	ds_read2_b32 v[44:45], v8 offset0:40 offset1:105
	ds_read2_b32 v[46:47], v8 offset0:170 offset1:235
	ds_read2_b32 v[48:49], v9 offset0:40 offset1:105
	ds_read2_b32 v[50:51], v9 offset0:170 offset1:235
	s_waitcnt lgkmcnt(4)
	v_cvt_pk_bf16_f32 v52, v36, v37
	v_cvt_pk_bf16_f32 v53, v38, v39
	v_cvt_pk_bf16_f32 v54, v40, v41
	v_cvt_pk_bf16_f32 v55, v42, v43
	global_store_dwordx4 v17, v[52:55], s[14:15] nt
	s_add_u32 s14, s14, s13
	s_addc_u32 s15, s15, 0
	ds_read2_b32 v[36:37], v8 offset0:48 offset1:113
	ds_read2_b32 v[38:39], v8 offset0:178 offset1:243
	ds_read2_b32 v[40:41], v9 offset0:48 offset1:113
	ds_read2_b32 v[42:43], v9 offset0:178 offset1:243
	s_waitcnt lgkmcnt(4)
	v_cvt_pk_bf16_f32 v56, v44, v45
	v_cvt_pk_bf16_f32 v57, v46, v47
	v_cvt_pk_bf16_f32 v58, v48, v49
	v_cvt_pk_bf16_f32 v59, v50, v51
	global_store_dwordx4 v17, v[56:59], s[14:15] nt
	s_add_u32 s14, s14, s13
	s_addc_u32 s15, s15, 0
	ds_read2_b32 v[44:45], v8 offset0:56 offset1:121
	ds_read2_b32 v[46:47], v8 offset0:186 offset1:251
	ds_read2_b32 v[48:49], v9 offset0:56 offset1:121
	ds_read2_b32 v[50:51], v9 offset0:186 offset1:251
	s_waitcnt lgkmcnt(4)
	v_cvt_pk_bf16_f32 v52, v36, v37
	v_cvt_pk_bf16_f32 v53, v38, v39
	v_cvt_pk_bf16_f32 v54, v40, v41
	v_cvt_pk_bf16_f32 v55, v42, v43
	global_store_dwordx4 v17, v[52:55], s[14:15] nt
	s_add_u32 s14, s14, s13
	s_addc_u32 s15, s15, 0
	s_waitcnt lgkmcnt(0)
	v_cvt_pk_bf16_f32 v56, v44, v45
	v_cvt_pk_bf16_f32 v57, v46, v47
	v_cvt_pk_bf16_f32 v58, v48, v49
	v_cvt_pk_bf16_f32 v59, v50, v51
	global_store_dwordx4 v17, v[56:59], s[14:15] nt
	s_add_i32 s13, s60, 0x1
	s_cmpk_lt_u32 s13, 0x1000
	s_cbranch_scc1 .Lcvi_dB1_c0
	s_cmpk_lt_u32 s13, 0x1400
	s_cbranch_scc1 .Lcvi_dB1_c1
	s_cmpk_lt_u32 s13, 0x2400
	s_cbranch_scc1 .Lcvi_dB1_c2
	s_add_i32 s13, s13, 0xffffdc00
	s_mov_b64 s[16:17], s[46:47]
	s_mov_b64 s[62:63], s[54:55]
	s_mov_b32 s14, 5
	s_mov_b32 s15, 19
	s_mov_b32 s19, 20
	s_mov_b32 s1, 13
	s_mov_b32 s12, 14
	s_branch .Lcvi_dB1_go
.Lcvi_dB1_c0:
	s_mov_b64 s[16:17], s[40:41]
	s_mov_b64 s[62:63], s[48:49]
	s_mov_b32 s14, 7
	s_mov_b32 s15, 21
	s_mov_b32 s19, 18
	s_mov_b32 s1, 15
	s_mov_b32 s12, 12
	s_branch .Lcvi_dB1_go
.Lcvi_dB1_c1:
	s_add_i32 s13, s13, 0xfffff000
	s_mov_b64 s[16:17], s[42:43]
	s_mov_b64 s[62:63], s[50:51]
	s_mov_b32 s14, 5
	s_mov_b32 s15, 19
	s_mov_b32 s19, 18
	s_mov_b32 s1, 13
	s_mov_b32 s12, 12
	s_branch .Lcvi_dB1_go
.Lcvi_dB1_c2:
	s_add_i32 s13, s13, 0xffffec00
	s_mov_b64 s[16:17], s[44:45]
	s_mov_b64 s[62:63], s[52:53]
	s_mov_b32 s14, 7
	s_mov_b32 s15, 21
	s_mov_b32 s19, 18
	s_mov_b32 s1, 15
	s_mov_b32 s12, 12
.Lcvi_dB1_go:
	s_lshr_b32 s0, s13, s14
	s_lshl_b32 s18, s0, s14
	s_sub_i32 s13, s13, s18
	s_lshl_b32 s18, s0, s15
	s_lshl_b32 s14, s13, 8
	s_add_i32 s18, s18, s14
	s_add_u32 s16, s16, s18
	s_addc_u32 s17, s17, 0
	s_lshl_b32 s18, s13, s19
	s_lshl_b32 s14, s0, 7
	s_add_i32 s18, s18, s14
	s_add_u32 s10, s62, s18
	s_addc_u32 s11, s63, 0
	s_add_i32 s18, s1, 2
	s_lshl_b32 s18, 1, s18
	v_lshlrev_b32_e32 v16, s1, v3
	v_or_b32_e32 v16, v16, v4
	global_load_dwordx4 v[136:139], v16, s[16:17] nt
	s_add_u32 s16, s16, s18
	s_addc_u32 s17, s17, 0
	global_load_dwordx4 v[140:143], v16, s[16:17] nt
	s_add_u32 s16, s16, s18
	s_addc_u32 s17, s17, 0
	global_load_dwordx4 v[144:147], v16, s[16:17] nt
	s_add_u32 s16, s16, s18
	s_addc_u32 s17, s17, 0
	global_load_dwordx4 v[148:151], v16, s[16:17] nt
	s_add_u32 s16, s16, s18
	s_addc_u32 s17, s17, 0
	global_load_dwordx4 v[152:155], v16, s[16:17] nt
	s_add_u32 s16, s16, s18
	s_addc_u32 s17, s17, 0
	global_load_dwordx4 v[156:159], v16, s[16:17] nt
	s_add_u32 s16, s16, s18
	s_addc_u32 s17, s17, 0
	global_load_dwordx4 v[160:163], v16, s[16:17] nt
	s_add_u32 s16, s16, s18
	s_addc_u32 s17, s17, 0
	global_load_dwordx4 v[164:167], v16, s[16:17] nt
	s_add_u32 s16, s16, s18
	s_addc_u32 s17, s17, 0
	global_load_dwordx4 v[168:171], v16, s[16:17] nt
	s_add_u32 s16, s16, s18
	s_addc_u32 s17, s17, 0
	global_load_dwordx4 v[172:175], v16, s[16:17] nt
	s_add_u32 s16, s16, s18
	s_addc_u32 s17, s17, 0
	global_load_dwordx4 v[176:179], v16, s[16:17] nt
	s_add_u32 s16, s16, s18
	s_addc_u32 s17, s17, 0
	global_load_dwordx4 v[180:183], v16, s[16:17] nt
	s_add_u32 s16, s16, s18
	s_addc_u32 s17, s17, 0
	global_load_dwordx4 v[184:187], v16, s[16:17] nt
	s_add_u32 s16, s16, s18
	s_addc_u32 s17, s17, 0
	global_load_dwordx4 v[188:191], v16, s[16:17] nt
	s_add_u32 s16, s16, s18
	s_addc_u32 s17, s17, 0
	global_load_dwordx4 v[192:195], v16, s[16:17] nt
	s_add_u32 s16, s16, s18
	s_addc_u32 s17, s17, 0
	global_load_dwordx4 v[196:199], v16, s[16:17] nt
	s_waitcnt vmcnt(24)
.Lcvi_pa0:
	ds_write_b32 v7, v72 offset:0
	ds_write_b32 v7, v73 offset:4
	ds_write_b32 v7, v74 offset:8
	ds_write_b32 v7, v75 offset:12
	ds_write_b32 v7, v76 offset:1040
	ds_write_b32 v7, v77 offset:1044
	ds_write_b32 v7, v78 offset:1048
	ds_write_b32 v7, v79 offset:1052
	ds_write_b32 v7, v80 offset:2080
	ds_write_b32 v7, v81 offset:2084
	ds_write_b32 v7, v82 offset:2088
	ds_write_b32 v7, v83 offset:2092
	ds_write_b32 v7, v84 offset:3120
	ds_write_b32 v7, v85 offset:3124
	ds_write_b32 v7, v86 offset:3128
	ds_write_b32 v7, v87 offset:3132
	ds_write_b32 v7, v88 offset:4160
	ds_write_b32 v7, v89 offset:4164
	ds_write_b32 v7, v90 offset:4168
	ds_write_b32 v7, v91 offset:4172
	ds_write_b32 v7, v92 offset:5200
	ds_write_b32 v7, v93 offset:5204
	ds_write_b32 v7, v94 offset:5208
	ds_write_b32 v7, v95 offset:5212
	ds_write_b32 v7, v96 offset:6240
	ds_write_b32 v7, v97 offset:6244
	ds_write_b32 v7, v98 offset:6248
	ds_write_b32 v7, v99 offset:6252
	ds_write_b32 v7, v100 offset:7280
	ds_write_b32 v7, v101 offset:7284
	ds_write_b32 v7, v102 offset:7288
	ds_write_b32 v7, v103 offset:7292
	ds_write_b32 v7, v104 offset:8320
	ds_write_b32 v7, v105 offset:8324
	ds_write_b32 v7, v106 offset:8328
	ds_write_b32 v7, v107 offset:8332
	ds_write_b32 v7, v108 offset:9360
	ds_write_b32 v7, v109 offset:9364
	ds_write_b32 v7, v110 offset:9368
	ds_write_b32 v7, v111 offset:9372
	ds_write_b32 v7, v112 offset:10400
	ds_write_b32 v7, v113 offset:10404
	ds_write_b32 v7, v114 offset:10408
	ds_write_b32 v7, v115 offset:10412
	ds_write_b32 v7, v116 offset:11440
	ds_write_b32 v7, v117 offset:11444
	ds_write_b32 v7, v118 offset:11448
	ds_write_b32 v7, v119 offset:11452
	ds_write_b32 v7, v120 offset:12480
	ds_write_b32 v7, v121 offset:12484
	ds_write_b32 v7, v122 offset:12488
	ds_write_b32 v7, v123 offset:12492
	ds_write_b32 v7, v124 offset:13520
	ds_write_b32 v7, v125 offset:13524
	ds_write_b32 v7, v126 offset:13528
	ds_write_b32 v7, v127 offset:13532
	ds_write_b32 v7, v128 offset:14560
	ds_write_b32 v7, v129 offset:14564
	ds_write_b32 v7, v130 offset:14568
	ds_write_b32 v7, v131 offset:14572
	ds_write_b32 v7, v132 offset:15600
	ds_write_b32 v7, v133 offset:15604
	ds_write_b32 v7, v134 offset:15608
	ds_write_b32 v7, v135 offset:15612
	v_lshlrev_b32_e32 v17, s8, v5
	v_or_b32_e32 v17, v17, v6
	s_lshl_b32 s13, 8, s8
	s_mov_b32 s14, s6
	s_mov_b32 s15, s7
	ds_read2_b32 v[36:37], v8 offset0:0 offset1:65
	ds_read2_b32 v[38:39], v8 offset0:130 offset1:195
	ds_read2_b32 v[40:41], v9 offset0:0 offset1:65
	ds_read2_b32 v[42:43], v9 offset0:130 offset1:195
	ds_read2_b32 v[44:45], v8 offset0:8 offset1:73
	ds_read2_b32 v[46:47], v8 offset0:138 offset1:203
	ds_read2_b32 v[48:49], v9 offset0:8 offset1:73
	ds_read2_b32 v[50:51], v9 offset0:138 offset1:203
	s_waitcnt lgkmcnt(4)
	v_cvt_pk_bf16_f32 v52, v36, v37
	v_cvt_pk_bf16_f32 v53, v38, v39
	v_cvt_pk_bf16_f32 v54, v40, v41
	v_cvt_pk_bf16_f32 v55, v42, v43
	global_store_dwordx4 v17, v[52:55], s[14:15] nt
	s_add_u32 s14, s14, s13
	s_addc_u32 s15, s15, 0
	ds_read2_b32 v[36:37], v8 offset0:16 offset1:81
	ds_read2_b32 v[38:39], v8 offset0:146 offset1:211
	ds_read2_b32 v[40:41], v9 offset0:16 offset1:81
	ds_read2_b32 v[42:43], v9 offset0:146 offset1:211
	s_waitcnt lgkmcnt(4)
	v_cvt_pk_bf16_f32 v56, v44, v45
	v_cvt_pk_bf16_f32 v57, v46, v47
	v_cvt_pk_bf16_f32 v58, v48, v49
	v_cvt_pk_bf16_f32 v59, v50, v51
	global_store_dwordx4 v17, v[56:59], s[14:15] nt
	s_add_u32 s14, s14, s13
	s_addc_u32 s15, s15, 0
	ds_read2_b32 v[44:45], v8 offset0:24 offset1:89
	ds_read2_b32 v[46:47], v8 offset0:154 offset1:219
	ds_read2_b32 v[48:49], v9 offset0:24 offset1:89
	ds_read2_b32 v[50:51], v9 offset0:154 offset1:219
	s_waitcnt lgkmcnt(4)
	v_cvt_pk_bf16_f32 v52, v36, v37
	v_cvt_pk_bf16_f32 v53, v38, v39
	v_cvt_pk_bf16_f32 v54, v40, v41
	v_cvt_pk_bf16_f32 v55, v42, v43
	global_store_dwordx4 v17, v[52:55], s[14:15] nt
	s_add_u32 s14, s14, s13
	s_addc_u32 s15, s15, 0
	ds_read2_b32 v[36:37], v8 offset0:32 offset1:97
	ds_read2_b32 v[38:39], v8 offset0:162 offset1:227
	ds_read2_b32 v[40:41], v9 offset0:32 offset1:97
	ds_read2_b32 v[42:43], v9 offset0:162 offset1:227
	s_waitcnt lgkmcnt(4)
	v_cvt_pk_bf16_f32 v56, v44, v45
	v_cvt_pk_bf16_f32 v57, v46, v47
	v_cvt_pk_bf16_f32 v58, v48, v49
	v_cvt_pk_bf16_f32 v59, v50, v51
	global_store_dwordx4 v17, v[56:59], s[14:15] nt
	s_add_u32 s14, s14, s13
	s_addc_u32 s15, s15, 0
	ds_read2_b32 v[44:45], v8 offset0:40 offset1:105
	ds_read2_b32 v[46:47], v8 offset0:170 offset1:235
	ds_read2_b32 v[48:49], v9 offset0:40 offset1:105
	ds_read2_b32 v[50:51], v9 offset0:170 offset1:235
	s_waitcnt lgkmcnt(4)
	v_cvt_pk_bf16_f32 v52, v36, v37
	v_cvt_pk_bf16_f32 v53, v38, v39
	v_cvt_pk_bf16_f32 v54, v40, v41
	v_cvt_pk_bf16_f32 v55, v42, v43
	global_store_dwordx4 v17, v[52:55], s[14:15] nt
	s_add_u32 s14, s14, s13
	s_addc_u32 s15, s15, 0
	ds_read2_b32 v[36:37], v8 offset0:48 offset1:113
	ds_read2_b32 v[38:39], v8 offset0:178 offset1:243
	ds_read2_b32 v[40:41], v9 offset0:48 offset1:113
	ds_read2_b32 v[42:43], v9 offset0:178 offset1:243
	s_waitcnt lgkmcnt(4)
	v_cvt_pk_bf16_f32 v56, v44, v45
	v_cvt_pk_bf16_f32 v57, v46, v47
	v_cvt_pk_bf16_f32 v58, v48, v49
	v_cvt_pk_bf16_f32 v59, v50, v51
	global_store_dwordx4 v17, v[56:59], s[14:15] nt
	s_add_u32 s14, s14, s13
	s_addc_u32 s15, s15, 0
	ds_read2_b32 v[44:45], v8 offset0:56 offset1:121
	ds_read2_b32 v[46:47], v8 offset0:186 offset1:251
	ds_read2_b32 v[48:49], v9 offset0:56 offset1:121
	ds_read2_b32 v[50:51], v9 offset0:186 offset1:251
	s_waitcnt lgkmcnt(4)
	v_cvt_pk_bf16_f32 v52, v36, v37
	v_cvt_pk_bf16_f32 v53, v38, v39
	v_cvt_pk_bf16_f32 v54, v40, v41
	v_cvt_pk_bf16_f32 v55, v42, v43
	global_store_dwordx4 v17, v[52:55], s[14:15] nt
	s_add_u32 s14, s14, s13
	s_addc_u32 s15, s15, 0
	s_waitcnt lgkmcnt(0)
	v_cvt_pk_bf16_f32 v56, v44, v45
	v_cvt_pk_bf16_f32 v57, v46, v47
	v_cvt_pk_bf16_f32 v58, v48, v49
	v_cvt_pk_bf16_f32 v59, v50, v51
	global_store_dwordx4 v17, v[56:59], s[14:15] nt
	s_add_i32 s13, s60, 0x2
	s_cmpk_lt_u32 s13, 0x1000
	s_cbranch_scc1 .Lcvi_dA2_c0
	s_cmpk_lt_u32 s13, 0x1400
	s_cbranch_scc1 .Lcvi_dA2_c1
	s_cmpk_lt_u32 s13, 0x2400
	s_cbranch_scc1 .Lcvi_dA2_c2
	s_add_i32 s13, s13, 0xffffdc00
	s_mov_b64 s[16:17], s[46:47]
	s_mov_b64 s[62:63], s[54:55]
	s_mov_b32 s14, 5
	s_mov_b32 s15, 19
	s_mov_b32 s19, 20
	s_mov_b32 s1, 13
	s_mov_b32 s8, 14
	s_branch .Lcvi_dA2_go

.Lcvi_dA2_go:
	s_lshr_b32 s0, s13, s14
	s_lshl_b32 s18, s0, s14
	s_sub_i32 s13, s13, s18
	s_lshl_b32 s18, s0, s15
	s_lshl_b32 s14, s13, 8
	s_add_i32 s18, s18, s14
	s_add_u32 s16, s16, s18
	s_addc_u32 s17, s17, 0
	s_lshl_b32 s18, s13, s19
	s_lshl_b32 s14, s0, 7
	s_add_i32 s18, s18, s14
	s_add_u32 s6, s62, s18
	s_addc_u32 s7, s63, 0
	s_add_i32 s18, s1, 2
	s_lshl_b32 s18, 1, s18
	v_lshlrev_b32_e32 v16, s1, v3
	v_or_b32_e32 v16, v16, v4
	global_load_dwordx4 v[72:75], v16, s[16:17] nt
	s_add_u32 s16, s16, s18
	s_addc_u32 s17, s17, 0
	global_load_dwordx4 v[76:79], v16, s[16:17] nt
	s_add_u32 s16, s16, s18
	s_addc_u32 s17, s17, 0
	global_load_dwordx4 v[80:83], v16, s[16:17] nt
	s_add_u32 s16, s16, s18
	s_addc_u32 s17, s17, 0
	global_load_dwordx4 v[84:87], v16, s[16:17] nt
	s_add_u32 s16, s16, s18
	s_addc_u32 s17, s17, 0
	global_load_dwordx4 v[88:91], v16, s[16:17] nt
	s_add_u32 s16, s16, s18
	s_addc_u32 s17, s17, 0
	global_load_dwordx4 v[92:95], v16, s[16:17] nt
	s_add_u32 s16, s16, s18
	s_addc_u32 s17, s17, 0
	global_load_dwordx4 v[96:99], v16, s[16:17] nt
	s_add_u32 s16, s16, s18
	s_addc_u32 s17, s17, 0
	global_load_dwordx4 v[100:103], v16, s[16:17] nt
	s_add_u32 s16, s16, s18
	s_addc_u32 s17, s17, 0
	global_load_dwordx4 v[104:107], v16, s[16:17] nt
	s_add_u32 s16, s16, s18
	s_addc_u32 s17, s17, 0
	global_load_dwordx4 v[108:111], v16, s[16:17] nt
	s_add_u32 s16, s16, s18
	s_addc_u32 s17, s17, 0
	global_load_dwordx4 v[112:115], v16, s[16:17] nt
	s_add_u32 s16, s16, s18
	s_addc_u32 s17, s17, 0
	global_load_dwordx4 v[116:119], v16, s[16:17] nt
	s_add_u32 s16, s16, s18
	s_addc_u32 s17, s17, 0
	global_load_dwordx4 v[120:123], v16, s[16:17] nt
	s_add_u32 s16, s16, s18
	s_addc_u32 s17, s17, 0
	global_load_dwordx4 v[124:127], v16, s[16:17] nt
	s_add_u32 s16, s16, s18
	s_addc_u32 s17, s17, 0
	global_load_dwordx4 v[128:131], v16, s[16:17] nt
	s_add_u32 s16, s16, s18
	s_addc_u32 s17, s17, 0
	global_load_dwordx4 v[132:135], v16, s[16:17] nt
	s_waitcnt vmcnt(24)
	ds_write_b32 v7, v136 offset:0
	ds_write_b32 v7, v137 offset:4
	ds_write_b32 v7, v138 offset:8
	ds_write_b32 v7, v139 offset:12
	ds_write_b32 v7, v140 offset:1040
	ds_write_b32 v7, v141 offset:1044
	ds_write_b32 v7, v142 offset:1048
	ds_write_b32 v7, v143 offset:1052
	ds_write_b32 v7, v144 offset:2080
	ds_write_b32 v7, v145 offset:2084
	ds_write_b32 v7, v146 offset:2088
	ds_write_b32 v7, v147 offset:2092
	ds_write_b32 v7, v148 offset:3120
	ds_write_b32 v7, v149 offset:3124
	ds_write_b32 v7, v150 offset:3128
	ds_write_b32 v7, v151 offset:3132
	ds_write_b32 v7, v152 offset:4160
	ds_write_b32 v7, v153 offset:4164
	ds_write_b32 v7, v154 offset:4168
	ds_write_b32 v7, v155 offset:4172
	ds_write_b32 v7, v156 offset:5200
	ds_write_b32 v7, v157 offset:5204
	ds_write_b32 v7, v158 offset:5208
	ds_write_b32 v7, v159 offset:5212
	ds_write_b32 v7, v160 offset:6240
	ds_write_b32 v7, v161 offset:6244
	ds_write_b32 v7, v162 offset:6248
	ds_write_b32 v7, v163 offset:6252
	ds_write_b32 v7, v164 offset:7280
	ds_write_b32 v7, v165 offset:7284
	ds_write_b32 v7, v166 offset:7288
	ds_write_b32 v7, v167 offset:7292
	ds_write_b32 v7, v168 offset:8320
	ds_write_b32 v7, v169 offset:8324
	ds_write_b32 v7, v170 offset:8328
	ds_write_b32 v7, v171 offset:8332
	ds_write_b32 v7, v172 offset:9360
	ds_write_b32 v7, v173 offset:9364
	ds_write_b32 v7, v174 offset:9368
	ds_write_b32 v7, v175 offset:9372
	ds_write_b32 v7, v176 offset:10400
	ds_write_b32 v7, v177 offset:10404
	ds_write_b32 v7, v178 offset:10408
	ds_write_b32 v7, v179 offset:10412
	ds_write_b32 v7, v180 offset:11440
	ds_write_b32 v7, v181 offset:11444
	ds_write_b32 v7, v182 offset:11448
	ds_write_b32 v7, v183 offset:11452
	ds_write_b32 v7, v184 offset:12480
	ds_write_b32 v7, v185 offset:12484
	ds_write_b32 v7, v186 offset:12488
	ds_write_b32 v7, v187 offset:12492
	ds_write_b32 v7, v188 offset:13520
	ds_write_b32 v7, v189 offset:13524
	ds_write_b32 v7, v190 offset:13528
	ds_write_b32 v7, v191 offset:13532
	ds_write_b32 v7, v192 offset:14560
	ds_write_b32 v7, v193 offset:14564
	ds_write_b32 v7, v194 offset:14568
	ds_write_b32 v7, v195 offset:14572
	ds_write_b32 v7, v196 offset:15600
	ds_write_b32 v7, v197 offset:15604
	ds_write_b32 v7, v198 offset:15608
	ds_write_b32 v7, v199 offset:15612
	v_lshlrev_b32_e32 v17, s12, v5
	v_or_b32_e32 v17, v17, v6
	s_lshl_b32 s13, 8, s12
	s_mov_b32 s14, s10
	s_mov_b32 s15, s11
	ds_read2_b32 v[36:37], v8 offset0:0 offset1:65
	ds_read2_b32 v[38:39], v8 offset0:130 offset1:195
	ds_read2_b32 v[40:41], v9 offset0:0 offset1:65
	ds_read2_b32 v[42:43], v9 offset0:130 offset1:195
	ds_read2_b32 v[44:45], v8 offset0:8 offset1:73
	ds_read2_b32 v[46:47], v8 offset0:138 offset1:203
	ds_read2_b32 v[48:49], v9 offset0:8 offset1:73
	ds_read2_b32 v[50:51], v9 offset0:138 offset1:203
	s_waitcnt lgkmcnt(4)
	v_cvt_pk_bf16_f32 v52, v36, v37
	v_cvt_pk_bf16_f32 v53, v38, v39
	v_cvt_pk_bf16_f32 v54, v40, v41
	v_cvt_pk_bf16_f32 v55, v42, v43
	global_store_dwordx4 v17, v[52:55], s[14:15] nt
	s_add_u32 s14, s14, s13
	s_addc_u32 s15, s15, 0
	ds_read2_b32 v[36:37], v8 offset0:16 offset1:81
	ds_read2_b32 v[38:39], v8 offset0:146 offset1:211
	ds_read2_b32 v[40:41], v9 offset0:16 offset1:81
	ds_read2_b32 v[42:43], v9 offset0:146 offset1:211
	s_waitcnt lgkmcnt(4)
	v_cvt_pk_bf16_f32 v56, v44, v45
	v_cvt_pk_bf16_f32 v57, v46, v47
	v_cvt_pk_bf16_f32 v58, v48, v49
	v_cvt_pk_bf16_f32 v59, v50, v51
	global_store_dwordx4 v17, v[56:59], s[14:15] nt
	s_add_u32 s14, s14, s13
	s_addc_u32 s15, s15, 0
	ds_read2_b32 v[44:45], v8 offset0:24 offset1:89
	ds_read2_b32 v[46:47], v8 offset0:154 offset1:219
	ds_read2_b32 v[48:49], v9 offset0:24 offset1:89
	ds_read2_b32 v[50:51], v9 offset0:154 offset1:219
	s_waitcnt lgkmcnt(4)
	v_cvt_pk_bf16_f32 v52, v36, v37
	v_cvt_pk_bf16_f32 v53, v38, v39
	v_cvt_pk_bf16_f32 v54, v40, v41
	v_cvt_pk_bf16_f32 v55, v42, v43
	global_store_dwordx4 v17, v[52:55], s[14:15] nt
	s_add_u32 s14, s14, s13
	s_addc_u32 s15, s15, 0
	ds_read2_b32 v[36:37], v8 offset0:32 offset1:97
	ds_read2_b32 v[38:39], v8 offset0:162 offset1:227
	ds_read2_b32 v[40:41], v9 offset0:32 offset1:97
	ds_read2_b32 v[42:43], v9 offset0:162 offset1:227
	s_waitcnt lgkmcnt(4)
	v_cvt_pk_bf16_f32 v56, v44, v45
	v_cvt_pk_bf16_f32 v57, v46, v47
	v_cvt_pk_bf16_f32 v58, v48, v49
	v_cvt_pk_bf16_f32 v59, v50, v51
	global_store_dwordx4 v17, v[56:59], s[14:15] nt
	s_add_u32 s14, s14, s13
	s_addc_u32 s15, s15, 0
	ds_read2_b32 v[44:45], v8 offset0:40 offset1:105
	ds_read2_b32 v[46:47], v8 offset0:170 offset1:235
	ds_read2_b32 v[48:49], v9 offset0:40 offset1:105
	ds_read2_b32 v[50:51], v9 offset0:170 offset1:235
	s_waitcnt lgkmcnt(4)
	v_cvt_pk_bf16_f32 v52, v36, v37
	v_cvt_pk_bf16_f32 v53, v38, v39
	v_cvt_pk_bf16_f32 v54, v40, v41
	v_cvt_pk_bf16_f32 v55, v42, v43
	global_store_dwordx4 v17, v[52:55], s[14:15] nt
	s_add_u32 s14, s14, s13
	s_addc_u32 s15, s15, 0
	ds_read2_b32 v[36:37], v8 offset0:48 offset1:113
	ds_read2_b32 v[38:39], v8 offset0:178 offset1:243
	ds_read2_b32 v[40:41], v9 offset0:48 offset1:113
	ds_read2_b32 v[42:43], v9 offset0:178 offset1:243
	s_waitcnt lgkmcnt(4)
	v_cvt_pk_bf16_f32 v56, v44, v45
	v_cvt_pk_bf16_f32 v57, v46, v47
	v_cvt_pk_bf16_f32 v58, v48, v49
	v_cvt_pk_bf16_f32 v59, v50, v51
	global_store_dwordx4 v17, v[56:59], s[14:15] nt
	s_add_u32 s14, s14, s13
	s_addc_u32 s15, s15, 0
	ds_read2_b32 v[44:45], v8 offset0:56 offset1:121
	ds_read2_b32 v[46:47], v8 offset0:186 offset1:251
	ds_read2_b32 v[48:49], v9 offset0:56 offset1:121
	ds_read2_b32 v[50:51], v9 offset0:186 offset1:251
	s_waitcnt lgkmcnt(4)
	v_cvt_pk_bf16_f32 v52, v36, v37
	v_cvt_pk_bf16_f32 v53, v38, v39
	v_cvt_pk_bf16_f32 v54, v40, v41
	v_cvt_pk_bf16_f32 v55, v42, v43
	global_store_dwordx4 v17, v[52:55], s[14:15] nt
	s_add_u32 s14, s14, s13
	s_addc_u32 s15, s15, 0
	s_waitcnt lgkmcnt(0)
	v_cvt_pk_bf16_f32 v56, v44, v45
	v_cvt_pk_bf16_f32 v57, v46, v47
	v_cvt_pk_bf16_f32 v58, v48, v49
	v_cvt_pk_bf16_f32 v59, v50, v51
	global_store_dwordx4 v17, v[56:59], s[14:15] nt
	s_add_i32 s13, s60, 0x3
	s_cmpk_lt_u32 s13, 0x1000
	s_cbranch_scc1 .Lcvi_dB3_c0
	s_cmpk_lt_u32 s13, 0x1400
	s_cbranch_scc1 .Lcvi_dB3_c1
	s_cmpk_lt_u32 s13, 0x2400
	s_cbranch_scc1 .Lcvi_dB3_c2
	s_add_i32 s13, s13, 0xffffdc00
	s_mov_b64 s[16:17], s[46:47]
	s_mov_b64 s[62:63], s[54:55]
	s_mov_b32 s14, 5
	s_mov_b32 s15, 19
	s_mov_b32 s19, 20
	s_mov_b32 s1, 13
	s_mov_b32 s12, 14
	s_branch .Lcvi_dB3_go

.Lcvi_dB3_go:
	s_lshr_b32 s0, s13, s14
	s_lshl_b32 s18, s0, s14
	s_sub_i32 s13, s13, s18
	s_lshl_b32 s18, s0, s15
	s_lshl_b32 s14, s13, 8
	s_add_i32 s18, s18, s14
	s_add_u32 s16, s16, s18
	s_addc_u32 s17, s17, 0
	s_lshl_b32 s18, s13, s19
	s_lshl_b32 s14, s0, 7
	s_add_i32 s18, s18, s14
	s_add_u32 s10, s62, s18
	s_addc_u32 s11, s63, 0
	s_add_i32 s18, s1, 2
	s_lshl_b32 s18, 1, s18
	v_lshlrev_b32_e32 v16, s1, v3
	v_or_b32_e32 v16, v16, v4
	global_load_dwordx4 v[136:139], v16, s[16:17] nt
	s_add_u32 s16, s16, s18
	s_addc_u32 s17, s17, 0
	global_load_dwordx4 v[140:143], v16, s[16:17] nt
	s_add_u32 s16, s16, s18
	s_addc_u32 s17, s17, 0
	global_load_dwordx4 v[144:147], v16, s[16:17] nt
	s_add_u32 s16, s16, s18
	s_addc_u32 s17, s17, 0
	global_load_dwordx4 v[148:151], v16, s[16:17] nt
	s_add_u32 s16, s16, s18
	s_addc_u32 s17, s17, 0
	global_load_dwordx4 v[152:155], v16, s[16:17] nt
	s_add_u32 s16, s16, s18
	s_addc_u32 s17, s17, 0
	global_load_dwordx4 v[156:159], v16, s[16:17] nt
	s_add_u32 s16, s16, s18
	s_addc_u32 s17, s17, 0
	global_load_dwordx4 v[160:163], v16, s[16:17] nt
	s_add_u32 s16, s16, s18
	s_addc_u32 s17, s17, 0
	global_load_dwordx4 v[164:167], v16, s[16:17] nt
	s_add_u32 s16, s16, s18
	s_addc_u32 s17, s17, 0
	global_load_dwordx4 v[168:171], v16, s[16:17] nt
	s_add_u32 s16, s16, s18
	s_addc_u32 s17, s17, 0
	global_load_dwordx4 v[172:175], v16, s[16:17] nt
	s_add_u32 s16, s16, s18
	s_addc_u32 s17, s17, 0
	global_load_dwordx4 v[176:179], v16, s[16:17] nt
	s_add_u32 s16, s16, s18
	s_addc_u32 s17, s17, 0
	global_load_dwordx4 v[180:183], v16, s[16:17] nt
	s_add_u32 s16, s16, s18
	s_addc_u32 s17, s17, 0
	global_load_dwordx4 v[184:187], v16, s[16:17] nt
	s_add_u32 s16, s16, s18
	s_addc_u32 s17, s17, 0
	global_load_dwordx4 v[188:191], v16, s[16:17] nt
	s_add_u32 s16, s16, s18
	s_addc_u32 s17, s17, 0
	global_load_dwordx4 v[192:195], v16, s[16:17] nt
	s_add_u32 s16, s16, s18
	s_addc_u32 s17, s17, 0
	global_load_dwordx4 v[196:199], v16, s[16:17] nt
	s_waitcnt vmcnt(24)
	ds_write_b32 v7, v72 offset:0
	ds_write_b32 v7, v73 offset:4
	ds_write_b32 v7, v74 offset:8
	ds_write_b32 v7, v75 offset:12
	ds_write_b32 v7, v76 offset:1040
	ds_write_b32 v7, v77 offset:1044
	ds_write_b32 v7, v78 offset:1048
	ds_write_b32 v7, v79 offset:1052
	ds_write_b32 v7, v80 offset:2080
	ds_write_b32 v7, v81 offset:2084
	ds_write_b32 v7, v82 offset:2088
	ds_write_b32 v7, v83 offset:2092
	ds_write_b32 v7, v84 offset:3120
	ds_write_b32 v7, v85 offset:3124
	ds_write_b32 v7, v86 offset:3128
	ds_write_b32 v7, v87 offset:3132
	ds_write_b32 v7, v88 offset:4160
	ds_write_b32 v7, v89 offset:4164
	ds_write_b32 v7, v90 offset:4168
	ds_write_b32 v7, v91 offset:4172
	ds_write_b32 v7, v92 offset:5200
	ds_write_b32 v7, v93 offset:5204
	ds_write_b32 v7, v94 offset:5208
	ds_write_b32 v7, v95 offset:5212
	ds_write_b32 v7, v96 offset:6240
	ds_write_b32 v7, v97 offset:6244
	ds_write_b32 v7, v98 offset:6248
	ds_write_b32 v7, v99 offset:6252
	ds_write_b32 v7, v100 offset:7280
	ds_write_b32 v7, v101 offset:7284
	ds_write_b32 v7, v102 offset:7288
	ds_write_b32 v7, v103 offset:7292
	ds_write_b32 v7, v104 offset:8320
	ds_write_b32 v7, v105 offset:8324
	ds_write_b32 v7, v106 offset:8328
	ds_write_b32 v7, v107 offset:8332
	ds_write_b32 v7, v108 offset:9360
	ds_write_b32 v7, v109 offset:9364
	ds_write_b32 v7, v110 offset:9368
	ds_write_b32 v7, v111 offset:9372
	ds_write_b32 v7, v112 offset:10400
	ds_write_b32 v7, v113 offset:10404
	ds_write_b32 v7, v114 offset:10408
	ds_write_b32 v7, v115 offset:10412
	ds_write_b32 v7, v116 offset:11440
	ds_write_b32 v7, v117 offset:11444
	ds_write_b32 v7, v118 offset:11448
	ds_write_b32 v7, v119 offset:11452
	ds_write_b32 v7, v120 offset:12480
	ds_write_b32 v7, v121 offset:12484
	ds_write_b32 v7, v122 offset:12488
	ds_write_b32 v7, v123 offset:12492
	ds_write_b32 v7, v124 offset:13520
	ds_write_b32 v7, v125 offset:13524
	ds_write_b32 v7, v126 offset:13528
	ds_write_b32 v7, v127 offset:13532
	ds_write_b32 v7, v128 offset:14560
	ds_write_b32 v7, v129 offset:14564
	ds_write_b32 v7, v130 offset:14568
	ds_write_b32 v7, v131 offset:14572
	ds_write_b32 v7, v132 offset:15600
	ds_write_b32 v7, v133 offset:15604
	ds_write_b32 v7, v134 offset:15608
	ds_write_b32 v7, v135 offset:15612
	v_lshlrev_b32_e32 v17, s8, v5
	v_or_b32_e32 v17, v17, v6
	s_lshl_b32 s13, 8, s8
	s_mov_b32 s14, s6
	s_mov_b32 s15, s7
	ds_read2_b32 v[36:37], v8 offset0:0 offset1:65
	ds_read2_b32 v[38:39], v8 offset0:130 offset1:195
	ds_read2_b32 v[40:41], v9 offset0:0 offset1:65
	ds_read2_b32 v[42:43], v9 offset0:130 offset1:195
	ds_read2_b32 v[44:45], v8 offset0:8 offset1:73
	ds_read2_b32 v[46:47], v8 offset0:138 offset1:203
	ds_read2_b32 v[48:49], v9 offset0:8 offset1:73
	ds_read2_b32 v[50:51], v9 offset0:138 offset1:203
	s_waitcnt lgkmcnt(4)
	v_cvt_pk_bf16_f32 v52, v36, v37
	v_cvt_pk_bf16_f32 v53, v38, v39
	v_cvt_pk_bf16_f32 v54, v40, v41
	v_cvt_pk_bf16_f32 v55, v42, v43
	global_store_dwordx4 v17, v[52:55], s[14:15] nt
	s_add_u32 s14, s14, s13
	s_addc_u32 s15, s15, 0
	ds_read2_b32 v[36:37], v8 offset0:16 offset1:81
	ds_read2_b32 v[38:39], v8 offset0:146 offset1:211
	ds_read2_b32 v[40:41], v9 offset0:16 offset1:81
	ds_read2_b32 v[42:43], v9 offset0:146 offset1:211
	s_waitcnt lgkmcnt(4)
	v_cvt_pk_bf16_f32 v56, v44, v45
	v_cvt_pk_bf16_f32 v57, v46, v47
	v_cvt_pk_bf16_f32 v58, v48, v49
	v_cvt_pk_bf16_f32 v59, v50, v51
	global_store_dwordx4 v17, v[56:59], s[14:15] nt
	s_add_u32 s14, s14, s13
	s_addc_u32 s15, s15, 0
	ds_read2_b32 v[44:45], v8 offset0:24 offset1:89
	ds_read2_b32 v[46:47], v8 offset0:154 offset1:219
	ds_read2_b32 v[48:49], v9 offset0:24 offset1:89
	ds_read2_b32 v[50:51], v9 offset0:154 offset1:219
	s_waitcnt lgkmcnt(4)
	v_cvt_pk_bf16_f32 v52, v36, v37
	v_cvt_pk_bf16_f32 v53, v38, v39
	v_cvt_pk_bf16_f32 v54, v40, v41
	v_cvt_pk_bf16_f32 v55, v42, v43
	global_store_dwordx4 v17, v[52:55], s[14:15] nt
	s_add_u32 s14, s14, s13
	s_addc_u32 s15, s15, 0
	ds_read2_b32 v[36:37], v8 offset0:32 offset1:97
	ds_read2_b32 v[38:39], v8 offset0:162 offset1:227
	ds_read2_b32 v[40:41], v9 offset0:32 offset1:97
	ds_read2_b32 v[42:43], v9 offset0:162 offset1:227
	s_waitcnt lgkmcnt(4)
	v_cvt_pk_bf16_f32 v56, v44, v45
	v_cvt_pk_bf16_f32 v57, v46, v47
	v_cvt_pk_bf16_f32 v58, v48, v49
	v_cvt_pk_bf16_f32 v59, v50, v51
	global_store_dwordx4 v17, v[56:59], s[14:15] nt
	s_add_u32 s14, s14, s13
	s_addc_u32 s15, s15, 0
	ds_read2_b32 v[44:45], v8 offset0:40 offset1:105
	ds_read2_b32 v[46:47], v8 offset0:170 offset1:235
	ds_read2_b32 v[48:49], v9 offset0:40 offset1:105
	ds_read2_b32 v[50:51], v9 offset0:170 offset1:235
	s_waitcnt lgkmcnt(4)
	v_cvt_pk_bf16_f32 v52, v36, v37
	v_cvt_pk_bf16_f32 v53, v38, v39
	v_cvt_pk_bf16_f32 v54, v40, v41
	v_cvt_pk_bf16_f32 v55, v42, v43
	global_store_dwordx4 v17, v[52:55], s[14:15] nt
	s_add_u32 s14, s14, s13
	s_addc_u32 s15, s15, 0
	ds_read2_b32 v[36:37], v8 offset0:48 offset1:113
	ds_read2_b32 v[38:39], v8 offset0:178 offset1:243
	ds_read2_b32 v[40:41], v9 offset0:48 offset1:113
	ds_read2_b32 v[42:43], v9 offset0:178 offset1:243
	s_waitcnt lgkmcnt(4)
	v_cvt_pk_bf16_f32 v56, v44, v45
	v_cvt_pk_bf16_f32 v57, v46, v47
	v_cvt_pk_bf16_f32 v58, v48, v49
	v_cvt_pk_bf16_f32 v59, v50, v51
	global_store_dwordx4 v17, v[56:59], s[14:15] nt
	s_add_u32 s14, s14, s13
	s_addc_u32 s15, s15, 0
	ds_read2_b32 v[44:45], v8 offset0:56 offset1:121
	ds_read2_b32 v[46:47], v8 offset0:186 offset1:251
	ds_read2_b32 v[48:49], v9 offset0:56 offset1:121
	ds_read2_b32 v[50:51], v9 offset0:186 offset1:251
	s_waitcnt lgkmcnt(4)
	v_cvt_pk_bf16_f32 v52, v36, v37
	v_cvt_pk_bf16_f32 v53, v38, v39
	v_cvt_pk_bf16_f32 v54, v40, v41
	v_cvt_pk_bf16_f32 v55, v42, v43
	global_store_dwordx4 v17, v[52:55], s[14:15] nt
	s_add_u32 s14, s14, s13
	s_addc_u32 s15, s15, 0
	s_waitcnt lgkmcnt(0)
	v_cvt_pk_bf16_f32 v56, v44, v45
	v_cvt_pk_bf16_f32 v57, v46, v47
	v_cvt_pk_bf16_f32 v58, v48, v49
	v_cvt_pk_bf16_f32 v59, v50, v51
	global_store_dwordx4 v17, v[56:59], s[14:15] nt
	v_readfirstlane_b32 s60, v19
	s_nop 3
	s_cmpk_lt_u32 s60, 0x1400
	s_cbranch_scc1 .Lcvi_grab
	s_waitcnt vmcnt(8)
	ds_write_b32 v7, v136 offset:0
	ds_write_b32 v7, v137 offset:4
	ds_write_b32 v7, v138 offset:8
	ds_write_b32 v7, v139 offset:12
	ds_write_b32 v7, v140 offset:1040
	ds_write_b32 v7, v141 offset:1044
	ds_write_b32 v7, v142 offset:1048
	ds_write_b32 v7, v143 offset:1052
	ds_write_b32 v7, v144 offset:2080
	ds_write_b32 v7, v145 offset:2084
	ds_write_b32 v7, v146 offset:2088
	ds_write_b32 v7, v147 offset:2092
	ds_write_b32 v7, v148 offset:3120
	ds_write_b32 v7, v149 offset:3124
	ds_write_b32 v7, v150 offset:3128
	ds_write_b32 v7, v151 offset:3132
	ds_write_b32 v7, v152 offset:4160
	ds_write_b32 v7, v153 offset:4164
	ds_write_b32 v7, v154 offset:4168
	ds_write_b32 v7, v155 offset:4172
	ds_write_b32 v7, v156 offset:5200
	ds_write_b32 v7, v157 offset:5204
	ds_write_b32 v7, v158 offset:5208
	ds_write_b32 v7, v159 offset:5212
	ds_write_b32 v7, v160 offset:6240
	ds_write_b32 v7, v161 offset:6244
	ds_write_b32 v7, v162 offset:6248
	ds_write_b32 v7, v163 offset:6252
	ds_write_b32 v7, v164 offset:7280
	ds_write_b32 v7, v165 offset:7284
	ds_write_b32 v7, v166 offset:7288
	ds_write_b32 v7, v167 offset:7292
	ds_write_b32 v7, v168 offset:8320
	ds_write_b32 v7, v169 offset:8324
	ds_write_b32 v7, v170 offset:8328
	ds_write_b32 v7, v171 offset:8332
	ds_write_b32 v7, v172 offset:9360
	ds_write_b32 v7, v173 offset:9364
	ds_write_b32 v7, v174 offset:9368
	ds_write_b32 v7, v175 offset:9372
	ds_write_b32 v7, v176 offset:10400
	ds_write_b32 v7, v177 offset:10404
	ds_write_b32 v7, v178 offset:10408
	ds_write_b32 v7, v179 offset:10412
	ds_write_b32 v7, v180 offset:11440
	ds_write_b32 v7, v181 offset:11444
	ds_write_b32 v7, v182 offset:11448
	ds_write_b32 v7, v183 offset:11452
	ds_write_b32 v7, v184 offset:12480
	ds_write_b32 v7, v185 offset:12484
	ds_write_b32 v7, v186 offset:12488
	ds_write_b32 v7, v187 offset:12492
	ds_write_b32 v7, v188 offset:13520
	ds_write_b32 v7, v189 offset:13524
	ds_write_b32 v7, v190 offset:13528
	ds_write_b32 v7, v191 offset:13532
	ds_write_b32 v7, v192 offset:14560
	ds_write_b32 v7, v193 offset:14564
	ds_write_b32 v7, v194 offset:14568
	ds_write_b32 v7, v195 offset:14572
	ds_write_b32 v7, v196 offset:15600
	ds_write_b32 v7, v197 offset:15604
	ds_write_b32 v7, v198 offset:15608
	ds_write_b32 v7, v199 offset:15612
	v_lshlrev_b32_e32 v17, s12, v5
	v_or_b32_e32 v17, v17, v6
	s_lshl_b32 s13, 8, s12
	s_mov_b32 s14, s10
	s_mov_b32 s15, s11
	ds_read2_b32 v[36:37], v8 offset0:0 offset1:65
	ds_read2_b32 v[38:39], v8 offset0:130 offset1:195
	ds_read2_b32 v[40:41], v9 offset0:0 offset1:65
	ds_read2_b32 v[42:43], v9 offset0:130 offset1:195
	ds_read2_b32 v[44:45], v8 offset0:8 offset1:73
	ds_read2_b32 v[46:47], v8 offset0:138 offset1:203
	ds_read2_b32 v[48:49], v9 offset0:8 offset1:73
	ds_read2_b32 v[50:51], v9 offset0:138 offset1:203
	s_waitcnt lgkmcnt(4)
	v_cvt_pk_bf16_f32 v52, v36, v37
	v_cvt_pk_bf16_f32 v53, v38, v39
	v_cvt_pk_bf16_f32 v54, v40, v41
	v_cvt_pk_bf16_f32 v55, v42, v43
	global_store_dwordx4 v17, v[52:55], s[14:15] nt
	s_add_u32 s14, s14, s13
	s_addc_u32 s15, s15, 0
	ds_read2_b32 v[36:37], v8 offset0:16 offset1:81
	ds_read2_b32 v[38:39], v8 offset0:146 offset1:211
	ds_read2_b32 v[40:41], v9 offset0:16 offset1:81
	ds_read2_b32 v[42:43], v9 offset0:146 offset1:211
	s_waitcnt lgkmcnt(4)
	v_cvt_pk_bf16_f32 v56, v44, v45
	v_cvt_pk_bf16_f32 v57, v46, v47
	v_cvt_pk_bf16_f32 v58, v48, v49
	v_cvt_pk_bf16_f32 v59, v50, v51
	global_store_dwordx4 v17, v[56:59], s[14:15] nt
	s_add_u32 s14, s14, s13
	s_addc_u32 s15, s15, 0
	ds_read2_b32 v[44:45], v8 offset0:24 offset1:89
	ds_read2_b32 v[46:47], v8 offset0:154 offset1:219
	ds_read2_b32 v[48:49], v9 offset0:24 offset1:89
	ds_read2_b32 v[50:51], v9 offset0:154 offset1:219
	s_waitcnt lgkmcnt(4)
	v_cvt_pk_bf16_f32 v52, v36, v37
	v_cvt_pk_bf16_f32 v53, v38, v39
	v_cvt_pk_bf16_f32 v54, v40, v41
	v_cvt_pk_bf16_f32 v55, v42, v43
	global_store_dwordx4 v17, v[52:55], s[14:15] nt
	s_add_u32 s14, s14, s13
	s_addc_u32 s15, s15, 0
	ds_read2_b32 v[36:37], v8 offset0:32 offset1:97
	ds_read2_b32 v[38:39], v8 offset0:162 offset1:227
	ds_read2_b32 v[40:41], v9 offset0:32 offset1:97
	ds_read2_b32 v[42:43], v9 offset0:162 offset1:227
	s_waitcnt lgkmcnt(4)
	v_cvt_pk_bf16_f32 v56, v44, v45
	v_cvt_pk_bf16_f32 v57, v46, v47
	v_cvt_pk_bf16_f32 v58, v48, v49
	v_cvt_pk_bf16_f32 v59, v50, v51
	global_store_dwordx4 v17, v[56:59], s[14:15] nt
	s_add_u32 s14, s14, s13
	s_addc_u32 s15, s15, 0
	ds_read2_b32 v[44:45], v8 offset0:40 offset1:105
	ds_read2_b32 v[46:47], v8 offset0:170 offset1:235
	ds_read2_b32 v[48:49], v9 offset0:40 offset1:105
	ds_read2_b32 v[50:51], v9 offset0:170 offset1:235
	s_waitcnt lgkmcnt(4)
	v_cvt_pk_bf16_f32 v52, v36, v37
	v_cvt_pk_bf16_f32 v53, v38, v39
	v_cvt_pk_bf16_f32 v54, v40, v41
	v_cvt_pk_bf16_f32 v55, v42, v43
	global_store_dwordx4 v17, v[52:55], s[14:15] nt
	s_add_u32 s14, s14, s13
	s_addc_u32 s15, s15, 0
	ds_read2_b32 v[36:37], v8 offset0:48 offset1:113
	ds_read2_b32 v[38:39], v8 offset0:178 offset1:243
	ds_read2_b32 v[40:41], v9 offset0:48 offset1:113
	ds_read2_b32 v[42:43], v9 offset0:178 offset1:243
	s_waitcnt lgkmcnt(4)
	v_cvt_pk_bf16_f32 v56, v44, v45
	v_cvt_pk_bf16_f32 v57, v46, v47
	v_cvt_pk_bf16_f32 v58, v48, v49
	v_cvt_pk_bf16_f32 v59, v50, v51
	global_store_dwordx4 v17, v[56:59], s[14:15] nt
	s_add_u32 s14, s14, s13
	s_addc_u32 s15, s15, 0
	ds_read2_b32 v[44:45], v8 offset0:56 offset1:121
	ds_read2_b32 v[46:47], v8 offset0:186 offset1:251
	ds_read2_b32 v[48:49], v9 offset0:56 offset1:121
	ds_read2_b32 v[50:51], v9 offset0:186 offset1:251
	s_waitcnt lgkmcnt(4)
	v_cvt_pk_bf16_f32 v52, v36, v37
	v_cvt_pk_bf16_f32 v53, v38, v39
	v_cvt_pk_bf16_f32 v54, v40, v41
	v_cvt_pk_bf16_f32 v55, v42, v43
	global_store_dwordx4 v17, v[52:55], s[14:15] nt
	s_add_u32 s14, s14, s13
	s_addc_u32 s15, s15, 0
	s_waitcnt lgkmcnt(0)
	v_cvt_pk_bf16_f32 v56, v44, v45
	v_cvt_pk_bf16_f32 v57, v46, v47
	v_cvt_pk_bf16_f32 v58, v48, v49
	v_cvt_pk_bf16_f32 v59, v50, v51
	global_store_dwordx4 v17, v[56:59], s[14:15] nt
	s_branch .Lcvi_done
.Lcvi_first:
	s_mov_b32 s61, 0
	s_add_i32 s13, s60, 0x1
	s_cmpk_lt_u32 s13, 0x1000
	s_cbranch_scc1 .Lcvi_dB4_c0
	s_cmpk_lt_u32 s13, 0x1400
	s_cbranch_scc1 .Lcvi_dB4_c1
	s_cmpk_lt_u32 s13, 0x2400
	s_cbranch_scc1 .Lcvi_dB4_c2
	s_add_i32 s13, s13, 0xffffdc00
	s_mov_b64 s[16:17], s[46:47]
	s_mov_b64 s[62:63], s[54:55]
	s_mov_b32 s14, 5
	s_mov_b32 s15, 19
	s_mov_b32 s19, 20
	s_mov_b32 s1, 13
	s_mov_b32 s12, 14
	s_branch .Lcvi_dB4_go

.Lcvi_dB4_go:
	s_lshr_b32 s0, s13, s14
	s_lshl_b32 s18, s0, s14
	s_sub_i32 s13, s13, s18
	s_lshl_b32 s18, s0, s15
	s_lshl_b32 s14, s13, 8
	s_add_i32 s18, s18, s14
	s_add_u32 s16, s16, s18
	s_addc_u32 s17, s17, 0
	s_lshl_b32 s18, s13, s19
	s_lshl_b32 s14, s0, 7
	s_add_i32 s18, s18, s14
	s_add_u32 s10, s62, s18
	s_addc_u32 s11, s63, 0
	s_add_i32 s18, s1, 2
	s_lshl_b32 s18, 1, s18
	v_lshlrev_b32_e32 v16, s1, v3
	v_or_b32_e32 v16, v16, v4
	global_load_dwordx4 v[136:139], v16, s[16:17] nt
	s_add_u32 s16, s16, s18
	s_addc_u32 s17, s17, 0
	global_load_dwordx4 v[140:143], v16, s[16:17] nt
	s_add_u32 s16, s16, s18
	s_addc_u32 s17, s17, 0
	global_load_dwordx4 v[144:147], v16, s[16:17] nt
	s_add_u32 s16, s16, s18
	s_addc_u32 s17, s17, 0
	global_load_dwordx4 v[148:151], v16, s[16:17] nt
	s_add_u32 s16, s16, s18
	s_addc_u32 s17, s17, 0
	global_load_dwordx4 v[152:155], v16, s[16:17] nt
	s_add_u32 s16, s16, s18
	s_addc_u32 s17, s17, 0
	global_load_dwordx4 v[156:159], v16, s[16:17] nt
	s_add_u32 s16, s16, s18
	s_addc_u32 s17, s17, 0
	global_load_dwordx4 v[160:163], v16, s[16:17] nt
	s_add_u32 s16, s16, s18
	s_addc_u32 s17, s17, 0
	global_load_dwordx4 v[164:167], v16, s[16:17] nt
	s_add_u32 s16, s16, s18
	s_addc_u32 s17, s17, 0
	global_load_dwordx4 v[168:171], v16, s[16:17] nt
	s_add_u32 s16, s16, s18
	s_addc_u32 s17, s17, 0
	global_load_dwordx4 v[172:175], v16, s[16:17] nt
	s_add_u32 s16, s16, s18
	s_addc_u32 s17, s17, 0
	global_load_dwordx4 v[176:179], v16, s[16:17] nt
	s_add_u32 s16, s16, s18
	s_addc_u32 s17, s17, 0
	global_load_dwordx4 v[180:183], v16, s[16:17] nt
	s_add_u32 s16, s16, s18
	s_addc_u32 s17, s17, 0
	global_load_dwordx4 v[184:187], v16, s[16:17] nt
	s_add_u32 s16, s16, s18
	s_addc_u32 s17, s17, 0
	global_load_dwordx4 v[188:191], v16, s[16:17] nt
	s_add_u32 s16, s16, s18
	s_addc_u32 s17, s17, 0
	global_load_dwordx4 v[192:195], v16, s[16:17] nt
	s_add_u32 s16, s16, s18
	s_addc_u32 s17, s17, 0
	global_load_dwordx4 v[196:199], v16, s[16:17] nt
	s_waitcnt vmcnt(16)
	s_branch .Lcvi_pa0
.Lcvi_done:
	s_waitcnt vmcnt(0) lgkmcnt(0)
	s_branch .LBB0_433
	s_waitcnt vmcnt(0)
	v_mov_b32_e32 v2, v0
	v_readlane_b32 s0, v253, 49
	v_readlane_b32 s1, v253, 50
	v_and_b32_e32 v68, 63, v2
	s_add_i32 s4, s0, 1
	v_readfirstlane_b32 s12, v2
	v_mov_b32_e32 v2, 0
	v_cmp_eq_u32_e64 s[38:39], 0, v68
	s_and_saveexec_b64 s[0:1], s[38:39]
	s_cbranch_execz .LBB0_385
	s_mov_b64 s[8:9], exec
	v_mbcnt_lo_u32_b32 v2, s8, 0
	v_mbcnt_hi_u32_b32 v2, s9, v2
	v_cmp_eq_u32_e32 vcc, 0, v2
	s_and_saveexec_b64 s[6:7], vcc
	s_cbranch_execz .LBB0_384
	s_lshl_b32 s10, s4, 6
	s_mov_b32 s11, s5
	s_lshl_b64 s[10:11], s[10:11], 2
	s_add_u32 s10, s26, s10
	s_addc_u32 s11, s27, s11
	s_bcnt1_i32_b64 s8, s[8:9]
	s_lshl_b32 s8, s8, 3
	v_mov_b32_e32 v3, s8
	global_atomic_add v3, v35, v3, s[10:11] offset:512 sc0

.LBB0_1394:
	s_andn2_b64 vcc, exec, s[0:1]
	s_cbranch_vccnz .LBB0_1543
	v_readlane_b32 s0, v253, 49
	v_readlane_b32 s1, v253, 50
	s_cmp_eq_u32 s0, 3
	v_readlane_b32 s0, v252, 0
	v_readlane_b32 s1, v255, 1
	s_cselect_b32 s60, s0, s1
	v_readlane_b32 s0, v253, 9
	v_readlane_b32 s1, v253, 10
	s_cmp_ge_i32 s0, s60
	s_mov_b64 s[0:1], -1
	s_cbranch_scc0 .LBB0_1453
	v_readlane_b32 s0, v253, 49
	v_readlane_b32 s6, v252, 1
	v_readlane_b32 s7, v252, 2
	s_nop 3
	s_add_i32 s4, s0, 1
	s_add_u32 s6, s6, 0xffffff58
	s_addc_u32 s7, s7, -1
	s_load_dwordx2 s[40:41], s[6:7], 0x58
	s_load_dwordx2 s[42:43], s[6:7], 0x70
	s_load_dwordx4 s[44:47], s[6:7], 0x78
	v_and_b32_e32 v2, 63, v0
	v_lshrrev_b32_e32 v3, 4, v2
	v_and_b32_e32 v4, 15, v2
	v_lshlrev_b32_e32 v4, 4, v4
	v_lshrrev_b32_e32 v5, 3, v2
	v_and_b32_e32 v6, 7, v2
	v_lshlrev_b32_e32 v6, 4, v6
	v_readfirstlane_b32 s0, v0
	s_nop 3
	s_lshr_b32 s0, s0, 6
	s_mulk_i32 s0, 0x4400
	v_mul_u32_u24_e32 v7, 0x104, v3
	v_add3_u32 v7, v7, v4, s0
	v_mul_u32_u24_e32 v8, 0x82, v6
	v_lshl_add_u32 v8, v5, 2, v8
	v_add_u32_e32 v8, s0, v8
	v_add_u32_e32 v9, 0x410, v8
	v_mov_b32_e32 v18, 0
	v_mov_b32_e32 v20, 4
	s_waitcnt lgkmcnt(0)
	s_lshl_b32 s0, s4, 26
	s_lshl_b32 s1, s4, 24
	s_add_u32 s40, s40, s0
	s_addc_u32 s41, s41, 0
	s_add_u32 s42, s42, s1
	s_addc_u32 s43, s43, 0
	s_add_u32 s44, s44, s0
	s_addc_u32 s45, s45, 0
	s_add_u32 s46, s46, s0
	s_addc_u32 s47, s47, 0
	s_lshl_b32 s0, s4, 25
	s_lshl_b32 s1, s4, 23
	s_add_u32 s48, s26, 0x200000
	s_addc_u32 s49, s27, 0
	s_add_u32 s48, s48, s0
	s_addc_u32 s49, s49, 0
	s_add_u32 s50, s26, 0x8200000
	s_addc_u32 s51, s27, 0
	s_add_u32 s50, s50, s1
	s_addc_u32 s51, s51, 0
	s_add_u32 s52, s26, 0xa200000
	s_addc_u32 s53, s27, 0
	s_add_u32 s52, s52, s0
	s_addc_u32 s53, s53, 0
	s_add_u32 s54, s26, 0x12200000
	s_addc_u32 s55, s27, 0
	s_add_u32 s54, s54, s0
	s_addc_u32 s55, s55, 0
	s_lshl_b32 s0, s4, 8
	s_add_u32 s56, s26, s0
	s_addc_u32 s57, s27, 0
	v_cmp_eq_u32_e32 vcc, 0, v2
	s_and_saveexec_b64 s[0:1], vcc
	global_atomic_add v19, v18, v20, s[56:57] offset:576 sc0
	s_or_b64 exec, exec, s[0:1]
	s_waitcnt vmcnt(0)
	v_readfirstlane_b32 s60, v19
	s_nop 3
	s_cmpk_lt_u32 s60, 0x2000
	s_cbranch_scc0 .Lcvu_done
	s_mov_b32 s61, 1
.Lcvu_grab:
	v_cmp_eq_u32_e32 vcc, 0, v2
	s_and_saveexec_b64 s[0:1], vcc
	global_atomic_add v19, v18, v20, s[56:57] offset:576 sc0
	s_or_b64 exec, exec, s[0:1]
	s_add_i32 s13, s60, 0x1400
	s_cmpk_lt_u32 s13, 0x1000
	s_cbranch_scc1 .Lcvu_dA0_c0
	s_cmpk_lt_u32 s13, 0x1400
	s_cbranch_scc1 .Lcvu_dA0_c1
	s_cmpk_lt_u32 s13, 0x2400
	s_cbranch_scc1 .Lcvu_dA0_c2
	s_add_i32 s13, s13, 0xffffdc00
	s_mov_b64 s[16:17], s[46:47]
	s_mov_b64 s[62:63], s[54:55]
	s_mov_b32 s14, 5
	s_mov_b32 s15, 19
	s_mov_b32 s19, 20
	s_mov_b32 s1, 13
	s_mov_b32 s8, 14
	s_branch .Lcvu_dA0_go

.Lcvu_dA0_go:
	s_lshr_b32 s0, s13, s14
	s_lshl_b32 s18, s0, s14
	s_sub_i32 s13, s13, s18
	s_lshl_b32 s18, s0, s15
	s_lshl_b32 s14, s13, 8
	s_add_i32 s18, s18, s14
	s_add_u32 s16, s16, s18
	s_addc_u32 s17, s17, 0
	s_lshl_b32 s18, s13, s19
	s_lshl_b32 s14, s0, 7
	s_add_i32 s18, s18, s14
	s_add_u32 s6, s62, s18
	s_addc_u32 s7, s63, 0
	s_add_i32 s18, s1, 2
	s_lshl_b32 s18, 1, s18
	v_lshlrev_b32_e32 v16, s1, v3
	v_or_b32_e32 v16, v16, v4
	global_load_dwordx4 v[72:75], v16, s[16:17] nt
	s_add_u32 s16, s16, s18
	s_addc_u32 s17, s17, 0
	global_load_dwordx4 v[76:79], v16, s[16:17] nt
	s_add_u32 s16, s16, s18
	s_addc_u32 s17, s17, 0
	global_load_dwordx4 v[80:83], v16, s[16:17] nt
	s_add_u32 s16, s16, s18
	s_addc_u32 s17, s17, 0
	global_load_dwordx4 v[84:87], v16, s[16:17] nt
	s_add_u32 s16, s16, s18
	s_addc_u32 s17, s17, 0
	global_load_dwordx4 v[88:91], v16, s[16:17] nt
	s_add_u32 s16, s16, s18
	s_addc_u32 s17, s17, 0
	global_load_dwordx4 v[92:95], v16, s[16:17] nt
	s_add_u32 s16, s16, s18
	s_addc_u32 s17, s17, 0
	global_load_dwordx4 v[96:99], v16, s[16:17] nt
	s_add_u32 s16, s16, s18
	s_addc_u32 s17, s17, 0
	global_load_dwordx4 v[100:103], v16, s[16:17] nt
	s_add_u32 s16, s16, s18
	s_addc_u32 s17, s17, 0
	global_load_dwordx4 v[104:107], v16, s[16:17] nt
	s_add_u32 s16, s16, s18
	s_addc_u32 s17, s17, 0
	global_load_dwordx4 v[108:111], v16, s[16:17] nt
	s_add_u32 s16, s16, s18
	s_addc_u32 s17, s17, 0
	global_load_dwordx4 v[112:115], v16, s[16:17] nt
	s_add_u32 s16, s16, s18
	s_addc_u32 s17, s17, 0
	global_load_dwordx4 v[116:119], v16, s[16:17] nt
	s_add_u32 s16, s16, s18
	s_addc_u32 s17, s17, 0
	global_load_dwordx4 v[120:123], v16, s[16:17] nt
	s_add_u32 s16, s16, s18
	s_addc_u32 s17, s17, 0
	global_load_dwordx4 v[124:127], v16, s[16:17] nt
	s_add_u32 s16, s16, s18
	s_addc_u32 s17, s17, 0
	global_load_dwordx4 v[128:131], v16, s[16:17] nt
	s_add_u32 s16, s16, s18
	s_addc_u32 s17, s17, 0
	global_load_dwordx4 v[132:135], v16, s[16:17] nt
	s_cmp_eq_u32 s61, 1
	s_cbranch_scc1 .Lcvu_first
	s_waitcnt vmcnt(25)
	ds_write_b32 v7, v136 offset:0
	ds_write_b32 v7, v137 offset:4
	ds_write_b32 v7, v138 offset:8
	ds_write_b32 v7, v139 offset:12
	ds_write_b32 v7, v140 offset:1040
	ds_write_b32 v7, v141 offset:1044
	ds_write_b32 v7, v142 offset:1048
	ds_write_b32 v7, v143 offset:1052
	ds_write_b32 v7, v144 offset:2080
	ds_write_b32 v7, v145 offset:2084
	ds_write_b32 v7, v146 offset:2088
	ds_write_b32 v7, v147 offset:2092
	ds_write_b32 v7, v148 offset:3120
	ds_write_b32 v7, v149 offset:3124
	ds_write_b32 v7, v150 offset:3128
	ds_write_b32 v7, v151 offset:3132
	ds_write_b32 v7, v152 offset:4160
	ds_write_b32 v7, v153 offset:4164
	ds_write_b32 v7, v154 offset:4168
	ds_write_b32 v7, v155 offset:4172
	ds_write_b32 v7, v156 offset:5200
	ds_write_b32 v7, v157 offset:5204
	ds_write_b32 v7, v158 offset:5208
	ds_write_b32 v7, v159 offset:5212
	ds_write_b32 v7, v160 offset:6240
	ds_write_b32 v7, v161 offset:6244
	ds_write_b32 v7, v162 offset:6248
	ds_write_b32 v7, v163 offset:6252
	ds_write_b32 v7, v164 offset:7280
	ds_write_b32 v7, v165 offset:7284
	ds_write_b32 v7, v166 offset:7288
	ds_write_b32 v7, v167 offset:7292
	ds_write_b32 v7, v168 offset:8320
	ds_write_b32 v7, v169 offset:8324
	ds_write_b32 v7, v170 offset:8328
	ds_write_b32 v7, v171 offset:8332
	ds_write_b32 v7, v172 offset:9360
	ds_write_b32 v7, v173 offset:9364
	ds_write_b32 v7, v174 offset:9368
	ds_write_b32 v7, v175 offset:9372
	ds_write_b32 v7, v176 offset:10400
	ds_write_b32 v7, v177 offset:10404
	ds_write_b32 v7, v178 offset:10408
	ds_write_b32 v7, v179 offset:10412
	ds_write_b32 v7, v180 offset:11440
	ds_write_b32 v7, v181 offset:11444
	ds_write_b32 v7, v182 offset:11448
	ds_write_b32 v7, v183 offset:11452
	ds_write_b32 v7, v184 offset:12480
	ds_write_b32 v7, v185 offset:12484
	ds_write_b32 v7, v186 offset:12488
	ds_write_b32 v7, v187 offset:12492
	ds_write_b32 v7, v188 offset:13520
	ds_write_b32 v7, v189 offset:13524
	ds_write_b32 v7, v190 offset:13528
	ds_write_b32 v7, v191 offset:13532
	ds_write_b32 v7, v192 offset:14560
	ds_write_b32 v7, v193 offset:14564
	ds_write_b32 v7, v194 offset:14568
	ds_write_b32 v7, v195 offset:14572
	ds_write_b32 v7, v196 offset:15600
	ds_write_b32 v7, v197 offset:15604
	ds_write_b32 v7, v198 offset:15608
	ds_write_b32 v7, v199 offset:15612
	v_lshlrev_b32_e32 v17, s12, v5
	v_or_b32_e32 v17, v17, v6
	s_lshl_b32 s13, 8, s12
	s_mov_b32 s14, s10
	s_mov_b32 s15, s11
	ds_read2_b32 v[36:37], v8 offset0:0 offset1:65
	ds_read2_b32 v[38:39], v8 offset0:130 offset1:195
	ds_read2_b32 v[40:41], v9 offset0:0 offset1:65
	ds_read2_b32 v[42:43], v9 offset0:130 offset1:195
	ds_read2_b32 v[44:45], v8 offset0:8 offset1:73
	ds_read2_b32 v[46:47], v8 offset0:138 offset1:203
	ds_read2_b32 v[48:49], v9 offset0:8 offset1:73
	ds_read2_b32 v[50:51], v9 offset0:138 offset1:203
	s_waitcnt lgkmcnt(4)
	v_cvt_pk_bf16_f32 v52, v36, v37
	v_cvt_pk_bf16_f32 v53, v38, v39
	v_cvt_pk_bf16_f32 v54, v40, v41
	v_cvt_pk_bf16_f32 v55, v42, v43
	global_store_dwordx4 v17, v[52:55], s[14:15] nt
	s_add_u32 s14, s14, s13
	s_addc_u32 s15, s15, 0
	ds_read2_b32 v[36:37], v8 offset0:16 offset1:81
	ds_read2_b32 v[38:39], v8 offset0:146 offset1:211
	ds_read2_b32 v[40:41], v9 offset0:16 offset1:81
	ds_read2_b32 v[42:43], v9 offset0:146 offset1:211
	s_waitcnt lgkmcnt(4)
	v_cvt_pk_bf16_f32 v56, v44, v45
	v_cvt_pk_bf16_f32 v57, v46, v47
	v_cvt_pk_bf16_f32 v58, v48, v49
	v_cvt_pk_bf16_f32 v59, v50, v51
	global_store_dwordx4 v17, v[56:59], s[14:15] nt
	s_add_u32 s14, s14, s13
	s_addc_u32 s15, s15, 0
	ds_read2_b32 v[44:45], v8 offset0:24 offset1:89
	ds_read2_b32 v[46:47], v8 offset0:154 offset1:219
	ds_read2_b32 v[48:49], v9 offset0:24 offset1:89
	ds_read2_b32 v[50:51], v9 offset0:154 offset1:219
	s_waitcnt lgkmcnt(4)
	v_cvt_pk_bf16_f32 v52, v36, v37
	v_cvt_pk_bf16_f32 v53, v38, v39
	v_cvt_pk_bf16_f32 v54, v40, v41
	v_cvt_pk_bf16_f32 v55, v42, v43
	global_store_dwordx4 v17, v[52:55], s[14:15] nt
	s_add_u32 s14, s14, s13
	s_addc_u32 s15, s15, 0
	ds_read2_b32 v[36:37], v8 offset0:32 offset1:97
	ds_read2_b32 v[38:39], v8 offset0:162 offset1:227
	ds_read2_b32 v[40:41], v9 offset0:32 offset1:97
	ds_read2_b32 v[42:43], v9 offset0:162 offset1:227
	s_waitcnt lgkmcnt(4)
	v_cvt_pk_bf16_f32 v56, v44, v45
	v_cvt_pk_bf16_f32 v57, v46, v47
	v_cvt_pk_bf16_f32 v58, v48, v49
	v_cvt_pk_bf16_f32 v59, v50, v51
	global_store_dwordx4 v17, v[56:59], s[14:15] nt
	s_add_u32 s14, s14, s13
	s_addc_u32 s15, s15, 0
	ds_read2_b32 v[44:45], v8 offset0:40 offset1:105
	ds_read2_b32 v[46:47], v8 offset0:170 offset1:235
	ds_read2_b32 v[48:49], v9 offset0:40 offset1:105
	ds_read2_b32 v[50:51], v9 offset0:170 offset1:235
	s_waitcnt lgkmcnt(4)
	v_cvt_pk_bf16_f32 v52, v36, v37
	v_cvt_pk_bf16_f32 v53, v38, v39
	v_cvt_pk_bf16_f32 v54, v40, v41
	v_cvt_pk_bf16_f32 v55, v42, v43
	global_store_dwordx4 v17, v[52:55], s[14:15] nt
	s_add_u32 s14, s14, s13
	s_addc_u32 s15, s15, 0
	ds_read2_b32 v[36:37], v8 offset0:48 offset1:113
	ds_read2_b32 v[38:39], v8 offset0:178 offset1:243
	ds_read2_b32 v[40:41], v9 offset0:48 offset1:113
	ds_read2_b32 v[42:43], v9 offset0:178 offset1:243
	s_waitcnt lgkmcnt(4)
	v_cvt_pk_bf16_f32 v56, v44, v45
	v_cvt_pk_bf16_f32 v57, v46, v47
	v_cvt_pk_bf16_f32 v58, v48, v49
	v_cvt_pk_bf16_f32 v59, v50, v51
	global_store_dwordx4 v17, v[56:59], s[14:15] nt
	s_add_u32 s14, s14, s13
	s_addc_u32 s15, s15, 0
	ds_read2_b32 v[44:45], v8 offset0:56 offset1:121
	ds_read2_b32 v[46:47], v8 offset0:186 offset1:251
	ds_read2_b32 v[48:49], v9 offset0:56 offset1:121
	ds_read2_b32 v[50:51], v9 offset0:186 offset1:251
	s_waitcnt lgkmcnt(4)
	v_cvt_pk_bf16_f32 v52, v36, v37
	v_cvt_pk_bf16_f32 v53, v38, v39
	v_cvt_pk_bf16_f32 v54, v40, v41
	v_cvt_pk_bf16_f32 v55, v42, v43
	global_store_dwordx4 v17, v[52:55], s[14:15] nt
	s_add_u32 s14, s14, s13
	s_addc_u32 s15, s15, 0
	s_waitcnt lgkmcnt(0)
	v_cvt_pk_bf16_f32 v56, v44, v45
	v_cvt_pk_bf16_f32 v57, v46, v47
	v_cvt_pk_bf16_f32 v58, v48, v49
	v_cvt_pk_bf16_f32 v59, v50, v51
	global_store_dwordx4 v17, v[56:59], s[14:15] nt
	s_add_i32 s13, s60, 0x1401
	s_cmpk_lt_u32 s13, 0x1000
	s_cbranch_scc1 .Lcvu_dB1_c0
	s_cmpk_lt_u32 s13, 0x1400
	s_cbranch_scc1 .Lcvu_dB1_c1
	s_cmpk_lt_u32 s13, 0x2400
	s_cbranch_scc1 .Lcvu_dB1_c2
	s_add_i32 s13, s13, 0xffffdc00
	s_mov_b64 s[16:17], s[46:47]
	s_mov_b64 s[62:63], s[54:55]
	s_mov_b32 s14, 5
	s_mov_b32 s15, 19
	s_mov_b32 s19, 20
	s_mov_b32 s1, 13
	s_mov_b32 s12, 14
	s_branch .Lcvu_dB1_go

.Lcvu_pa0:
	ds_write_b32 v7, v72 offset:0
	ds_write_b32 v7, v73 offset:4
	ds_write_b32 v7, v74 offset:8
	ds_write_b32 v7, v75 offset:12
	ds_write_b32 v7, v76 offset:1040
	ds_write_b32 v7, v77 offset:1044
	ds_write_b32 v7, v78 offset:1048
	ds_write_b32 v7, v79 offset:1052
	ds_write_b32 v7, v80 offset:2080
	ds_write_b32 v7, v81 offset:2084
	ds_write_b32 v7, v82 offset:2088
	ds_write_b32 v7, v83 offset:2092
	ds_write_b32 v7, v84 offset:3120
	ds_write_b32 v7, v85 offset:3124
	ds_write_b32 v7, v86 offset:3128
	ds_write_b32 v7, v87 offset:3132
	ds_write_b32 v7, v88 offset:4160
	ds_write_b32 v7, v89 offset:4164
	ds_write_b32 v7, v90 offset:4168
	ds_write_b32 v7, v91 offset:4172
	ds_write_b32 v7, v92 offset:5200
	ds_write_b32 v7, v93 offset:5204
	ds_write_b32 v7, v94 offset:5208
	ds_write_b32 v7, v95 offset:5212
	ds_write_b32 v7, v96 offset:6240
	ds_write_b32 v7, v97 offset:6244
	ds_write_b32 v7, v98 offset:6248
	ds_write_b32 v7, v99 offset:6252
	ds_write_b32 v7, v100 offset:7280
	ds_write_b32 v7, v101 offset:7284
	ds_write_b32 v7, v102 offset:7288
	ds_write_b32 v7, v103 offset:7292
	ds_write_b32 v7, v104 offset:8320
	ds_write_b32 v7, v105 offset:8324
	ds_write_b32 v7, v106 offset:8328
	ds_write_b32 v7, v107 offset:8332
	ds_write_b32 v7, v108 offset:9360
	ds_write_b32 v7, v109 offset:9364
	ds_write_b32 v7, v110 offset:9368
	ds_write_b32 v7, v111 offset:9372
	ds_write_b32 v7, v112 offset:10400
	ds_write_b32 v7, v113 offset:10404
	ds_write_b32 v7, v114 offset:10408
	ds_write_b32 v7, v115 offset:10412
	ds_write_b32 v7, v116 offset:11440
	ds_write_b32 v7, v117 offset:11444
	ds_write_b32 v7, v118 offset:11448
	ds_write_b32 v7, v119 offset:11452
	ds_write_b32 v7, v120 offset:12480
	ds_write_b32 v7, v121 offset:12484
	ds_write_b32 v7, v122 offset:12488
	ds_write_b32 v7, v123 offset:12492
	ds_write_b32 v7, v124 offset:13520
	ds_write_b32 v7, v125 offset:13524
	ds_write_b32 v7, v126 offset:13528
	ds_write_b32 v7, v127 offset:13532
	ds_write_b32 v7, v128 offset:14560
	ds_write_b32 v7, v129 offset:14564
	ds_write_b32 v7, v130 offset:14568
	ds_write_b32 v7, v131 offset:14572
	ds_write_b32 v7, v132 offset:15600
	ds_write_b32 v7, v133 offset:15604
	ds_write_b32 v7, v134 offset:15608
	ds_write_b32 v7, v135 offset:15612
	v_lshlrev_b32_e32 v17, s8, v5
	v_or_b32_e32 v17, v17, v6
	s_lshl_b32 s13, 8, s8
	s_mov_b32 s14, s6
	s_mov_b32 s15, s7
	ds_read2_b32 v[36:37], v8 offset0:0 offset1:65
	ds_read2_b32 v[38:39], v8 offset0:130 offset1:195
	ds_read2_b32 v[40:41], v9 offset0:0 offset1:65
	ds_read2_b32 v[42:43], v9 offset0:130 offset1:195
	ds_read2_b32 v[44:45], v8 offset0:8 offset1:73
	ds_read2_b32 v[46:47], v8 offset0:138 offset1:203
	ds_read2_b32 v[48:49], v9 offset0:8 offset1:73
	ds_read2_b32 v[50:51], v9 offset0:138 offset1:203
	s_waitcnt lgkmcnt(4)
	v_cvt_pk_bf16_f32 v52, v36, v37
	v_cvt_pk_bf16_f32 v53, v38, v39
	v_cvt_pk_bf16_f32 v54, v40, v41
	v_cvt_pk_bf16_f32 v55, v42, v43
	global_store_dwordx4 v17, v[52:55], s[14:15] nt
	s_add_u32 s14, s14, s13
	s_addc_u32 s15, s15, 0
	ds_read2_b32 v[36:37], v8 offset0:16 offset1:81
	ds_read2_b32 v[38:39], v8 offset0:146 offset1:211
	ds_read2_b32 v[40:41], v9 offset0:16 offset1:81
	ds_read2_b32 v[42:43], v9 offset0:146 offset1:211
	s_waitcnt lgkmcnt(4)
	v_cvt_pk_bf16_f32 v56, v44, v45
	v_cvt_pk_bf16_f32 v57, v46, v47
	v_cvt_pk_bf16_f32 v58, v48, v49
	v_cvt_pk_bf16_f32 v59, v50, v51
	global_store_dwordx4 v17, v[56:59], s[14:15] nt
	s_add_u32 s14, s14, s13
	s_addc_u32 s15, s15, 0
	ds_read2_b32 v[44:45], v8 offset0:24 offset1:89
	ds_read2_b32 v[46:47], v8 offset0:154 offset1:219
	ds_read2_b32 v[48:49], v9 offset0:24 offset1:89
	ds_read2_b32 v[50:51], v9 offset0:154 offset1:219
	s_waitcnt lgkmcnt(4)
	v_cvt_pk_bf16_f32 v52, v36, v37
	v_cvt_pk_bf16_f32 v53, v38, v39
	v_cvt_pk_bf16_f32 v54, v40, v41
	v_cvt_pk_bf16_f32 v55, v42, v43
	global_store_dwordx4 v17, v[52:55], s[14:15] nt
	s_add_u32 s14, s14, s13
	s_addc_u32 s15, s15, 0
	ds_read2_b32 v[36:37], v8 offset0:32 offset1:97
	ds_read2_b32 v[38:39], v8 offset0:162 offset1:227
	ds_read2_b32 v[40:41], v9 offset0:32 offset1:97
	ds_read2_b32 v[42:43], v9 offset0:162 offset1:227
	s_waitcnt lgkmcnt(4)
	v_cvt_pk_bf16_f32 v56, v44, v45
	v_cvt_pk_bf16_f32 v57, v46, v47
	v_cvt_pk_bf16_f32 v58, v48, v49
	v_cvt_pk_bf16_f32 v59, v50, v51
	global_store_dwordx4 v17, v[56:59], s[14:15] nt
	s_add_u32 s14, s14, s13
	s_addc_u32 s15, s15, 0
	ds_read2_b32 v[44:45], v8 offset0:40 offset1:105
	ds_read2_b32 v[46:47], v8 offset0:170 offset1:235
	ds_read2_b32 v[48:49], v9 offset0:40 offset1:105
	ds_read2_b32 v[50:51], v9 offset0:170 offset1:235
	s_waitcnt lgkmcnt(4)
	v_cvt_pk_bf16_f32 v52, v36, v37
	v_cvt_pk_bf16_f32 v53, v38, v39
	v_cvt_pk_bf16_f32 v54, v40, v41
	v_cvt_pk_bf16_f32 v55, v42, v43
	global_store_dwordx4 v17, v[52:55], s[14:15] nt
	s_add_u32 s14, s14, s13
	s_addc_u32 s15, s15, 0
	ds_read2_b32 v[36:37], v8 offset0:48 offset1:113
	ds_read2_b32 v[38:39], v8 offset0:178 offset1:243
	ds_read2_b32 v[40:41], v9 offset0:48 offset1:113
	ds_read2_b32 v[42:43], v9 offset0:178 offset1:243
	s_waitcnt lgkmcnt(4)
	v_cvt_pk_bf16_f32 v56, v44, v45
	v_cvt_pk_bf16_f32 v57, v46, v47
	v_cvt_pk_bf16_f32 v58, v48, v49
	v_cvt_pk_bf16_f32 v59, v50, v51
	global_store_dwordx4 v17, v[56:59], s[14:15] nt
	s_add_u32 s14, s14, s13
	s_addc_u32 s15, s15, 0
	ds_read2_b32 v[44:45], v8 offset0:56 offset1:121
	ds_read2_b32 v[46:47], v8 offset0:186 offset1:251
	ds_read2_b32 v[48:49], v9 offset0:56 offset1:121
	ds_read2_b32 v[50:51], v9 offset0:186 offset1:251
	s_waitcnt lgkmcnt(4)
	v_cvt_pk_bf16_f32 v52, v36, v37
	v_cvt_pk_bf16_f32 v53, v38, v39
	v_cvt_pk_bf16_f32 v54, v40, v41
	v_cvt_pk_bf16_f32 v55, v42, v43
	global_store_dwordx4 v17, v[52:55], s[14:15] nt
	s_add_u32 s14, s14, s13
	s_addc_u32 s15, s15, 0
	s_waitcnt lgkmcnt(0)
	v_cvt_pk_bf16_f32 v56, v44, v45
	v_cvt_pk_bf16_f32 v57, v46, v47
	v_cvt_pk_bf16_f32 v58, v48, v49
	v_cvt_pk_bf16_f32 v59, v50, v51
	global_store_dwordx4 v17, v[56:59], s[14:15] nt
	s_add_i32 s13, s60, 0x1402
	s_cmpk_lt_u32 s13, 0x1000
	s_cbranch_scc1 .Lcvu_dA2_c0
	s_cmpk_lt_u32 s13, 0x1400
	s_cbranch_scc1 .Lcvu_dA2_c1
	s_cmpk_lt_u32 s13, 0x2400
	s_cbranch_scc1 .Lcvu_dA2_c2
	s_add_i32 s13, s13, 0xffffdc00
	s_mov_b64 s[16:17], s[46:47]
	s_mov_b64 s[62:63], s[54:55]
	s_mov_b32 s14, 5
	s_mov_b32 s15, 19
	s_mov_b32 s19, 20
	s_mov_b32 s1, 13
	s_mov_b32 s8, 14
	s_branch .Lcvu_dA2_go

.Lcvu_dA2_go:
	s_lshr_b32 s0, s13, s14
	s_lshl_b32 s18, s0, s14
	s_sub_i32 s13, s13, s18
	s_lshl_b32 s18, s0, s15
	s_lshl_b32 s14, s13, 8
	s_add_i32 s18, s18, s14
	s_add_u32 s16, s16, s18
	s_addc_u32 s17, s17, 0
	s_lshl_b32 s18, s13, s19
	s_lshl_b32 s14, s0, 7
	s_add_i32 s18, s18, s14
	s_add_u32 s6, s62, s18
	s_addc_u32 s7, s63, 0
	s_add_i32 s18, s1, 2
	s_lshl_b32 s18, 1, s18
	v_lshlrev_b32_e32 v16, s1, v3
	v_or_b32_e32 v16, v16, v4
	global_load_dwordx4 v[72:75], v16, s[16:17] nt
	s_add_u32 s16, s16, s18
	s_addc_u32 s17, s17, 0
	global_load_dwordx4 v[76:79], v16, s[16:17] nt
	s_add_u32 s16, s16, s18
	s_addc_u32 s17, s17, 0
	global_load_dwordx4 v[80:83], v16, s[16:17] nt
	s_add_u32 s16, s16, s18
	s_addc_u32 s17, s17, 0
	global_load_dwordx4 v[84:87], v16, s[16:17] nt
	s_add_u32 s16, s16, s18
	s_addc_u32 s17, s17, 0
	global_load_dwordx4 v[88:91], v16, s[16:17] nt
	s_add_u32 s16, s16, s18
	s_addc_u32 s17, s17, 0
	global_load_dwordx4 v[92:95], v16, s[16:17] nt
	s_add_u32 s16, s16, s18
	s_addc_u32 s17, s17, 0
	global_load_dwordx4 v[96:99], v16, s[16:17] nt
	s_add_u32 s16, s16, s18
	s_addc_u32 s17, s17, 0
	global_load_dwordx4 v[100:103], v16, s[16:17] nt
	s_add_u32 s16, s16, s18
	s_addc_u32 s17, s17, 0
	global_load_dwordx4 v[104:107], v16, s[16:17] nt
	s_add_u32 s16, s16, s18
	s_addc_u32 s17, s17, 0
	global_load_dwordx4 v[108:111], v16, s[16:17] nt
	s_add_u32 s16, s16, s18
	s_addc_u32 s17, s17, 0
	global_load_dwordx4 v[112:115], v16, s[16:17] nt
	s_add_u32 s16, s16, s18
	s_addc_u32 s17, s17, 0
	global_load_dwordx4 v[116:119], v16, s[16:17] nt
	s_add_u32 s16, s16, s18
	s_addc_u32 s17, s17, 0
	global_load_dwordx4 v[120:123], v16, s[16:17] nt
	s_add_u32 s16, s16, s18
	s_addc_u32 s17, s17, 0
	global_load_dwordx4 v[124:127], v16, s[16:17] nt
	s_add_u32 s16, s16, s18
	s_addc_u32 s17, s17, 0
	global_load_dwordx4 v[128:131], v16, s[16:17] nt
	s_add_u32 s16, s16, s18
	s_addc_u32 s17, s17, 0
	global_load_dwordx4 v[132:135], v16, s[16:17] nt
	s_waitcnt vmcnt(24)
	ds_write_b32 v7, v136 offset:0
	ds_write_b32 v7, v137 offset:4
	ds_write_b32 v7, v138 offset:8
	ds_write_b32 v7, v139 offset:12
	ds_write_b32 v7, v140 offset:1040
	ds_write_b32 v7, v141 offset:1044
	ds_write_b32 v7, v142 offset:1048
	ds_write_b32 v7, v143 offset:1052
	ds_write_b32 v7, v144 offset:2080
	ds_write_b32 v7, v145 offset:2084
	ds_write_b32 v7, v146 offset:2088
	ds_write_b32 v7, v147 offset:2092
	ds_write_b32 v7, v148 offset:3120
	ds_write_b32 v7, v149 offset:3124
	ds_write_b32 v7, v150 offset:3128
	ds_write_b32 v7, v151 offset:3132
	ds_write_b32 v7, v152 offset:4160
	ds_write_b32 v7, v153 offset:4164
	ds_write_b32 v7, v154 offset:4168
	ds_write_b32 v7, v155 offset:4172
	ds_write_b32 v7, v156 offset:5200
	ds_write_b32 v7, v157 offset:5204
	ds_write_b32 v7, v158 offset:5208
	ds_write_b32 v7, v159 offset:5212
	ds_write_b32 v7, v160 offset:6240
	ds_write_b32 v7, v161 offset:6244
	ds_write_b32 v7, v162 offset:6248
	ds_write_b32 v7, v163 offset:6252
	ds_write_b32 v7, v164 offset:7280
	ds_write_b32 v7, v165 offset:7284
	ds_write_b32 v7, v166 offset:7288
	ds_write_b32 v7, v167 offset:7292
	ds_write_b32 v7, v168 offset:8320
	ds_write_b32 v7, v169 offset:8324
	ds_write_b32 v7, v170 offset:8328
	ds_write_b32 v7, v171 offset:8332
	ds_write_b32 v7, v172 offset:9360
	ds_write_b32 v7, v173 offset:9364
	ds_write_b32 v7, v174 offset:9368
	ds_write_b32 v7, v175 offset:9372
	ds_write_b32 v7, v176 offset:10400
	ds_write_b32 v7, v177 offset:10404
	ds_write_b32 v7, v178 offset:10408
	ds_write_b32 v7, v179 offset:10412
	ds_write_b32 v7, v180 offset:11440
	ds_write_b32 v7, v181 offset:11444
	ds_write_b32 v7, v182 offset:11448
	ds_write_b32 v7, v183 offset:11452
	ds_write_b32 v7, v184 offset:12480
	ds_write_b32 v7, v185 offset:12484
	ds_write_b32 v7, v186 offset:12488
	ds_write_b32 v7, v187 offset:12492
	ds_write_b32 v7, v188 offset:13520
	ds_write_b32 v7, v189 offset:13524
	ds_write_b32 v7, v190 offset:13528
	ds_write_b32 v7, v191 offset:13532
	ds_write_b32 v7, v192 offset:14560
	ds_write_b32 v7, v193 offset:14564
	ds_write_b32 v7, v194 offset:14568
	ds_write_b32 v7, v195 offset:14572
	ds_write_b32 v7, v196 offset:15600
	ds_write_b32 v7, v197 offset:15604
	ds_write_b32 v7, v198 offset:15608
	ds_write_b32 v7, v199 offset:15612
	v_lshlrev_b32_e32 v17, s12, v5
	v_or_b32_e32 v17, v17, v6
	s_lshl_b32 s13, 8, s12
	s_mov_b32 s14, s10
	s_mov_b32 s15, s11
	ds_read2_b32 v[36:37], v8 offset0:0 offset1:65
	ds_read2_b32 v[38:39], v8 offset0:130 offset1:195
	ds_read2_b32 v[40:41], v9 offset0:0 offset1:65
	ds_read2_b32 v[42:43], v9 offset0:130 offset1:195
	ds_read2_b32 v[44:45], v8 offset0:8 offset1:73
	ds_read2_b32 v[46:47], v8 offset0:138 offset1:203
	ds_read2_b32 v[48:49], v9 offset0:8 offset1:73
	ds_read2_b32 v[50:51], v9 offset0:138 offset1:203
	s_waitcnt lgkmcnt(4)
	v_cvt_pk_bf16_f32 v52, v36, v37
	v_cvt_pk_bf16_f32 v53, v38, v39
	v_cvt_pk_bf16_f32 v54, v40, v41
	v_cvt_pk_bf16_f32 v55, v42, v43
	global_store_dwordx4 v17, v[52:55], s[14:15] nt
	s_add_u32 s14, s14, s13
	s_addc_u32 s15, s15, 0
	ds_read2_b32 v[36:37], v8 offset0:16 offset1:81
	ds_read2_b32 v[38:39], v8 offset0:146 offset1:211
	ds_read2_b32 v[40:41], v9 offset0:16 offset1:81
	ds_read2_b32 v[42:43], v9 offset0:146 offset1:211
	s_waitcnt lgkmcnt(4)
	v_cvt_pk_bf16_f32 v56, v44, v45
	v_cvt_pk_bf16_f32 v57, v46, v47
	v_cvt_pk_bf16_f32 v58, v48, v49
	v_cvt_pk_bf16_f32 v59, v50, v51
	global_store_dwordx4 v17, v[56:59], s[14:15] nt
	s_add_u32 s14, s14, s13
	s_addc_u32 s15, s15, 0
	ds_read2_b32 v[44:45], v8 offset0:24 offset1:89
	ds_read2_b32 v[46:47], v8 offset0:154 offset1:219
	ds_read2_b32 v[48:49], v9 offset0:24 offset1:89
	ds_read2_b32 v[50:51], v9 offset0:154 offset1:219
	s_waitcnt lgkmcnt(4)
	v_cvt_pk_bf16_f32 v52, v36, v37
	v_cvt_pk_bf16_f32 v53, v38, v39
	v_cvt_pk_bf16_f32 v54, v40, v41
	v_cvt_pk_bf16_f32 v55, v42, v43
	global_store_dwordx4 v17, v[52:55], s[14:15] nt
	s_add_u32 s14, s14, s13
	s_addc_u32 s15, s15, 0
	ds_read2_b32 v[36:37], v8 offset0:32 offset1:97
	ds_read2_b32 v[38:39], v8 offset0:162 offset1:227
	ds_read2_b32 v[40:41], v9 offset0:32 offset1:97
	ds_read2_b32 v[42:43], v9 offset0:162 offset1:227
	s_waitcnt lgkmcnt(4)
	v_cvt_pk_bf16_f32 v56, v44, v45
	v_cvt_pk_bf16_f32 v57, v46, v47
	v_cvt_pk_bf16_f32 v58, v48, v49
	v_cvt_pk_bf16_f32 v59, v50, v51
	global_store_dwordx4 v17, v[56:59], s[14:15] nt
	s_add_u32 s14, s14, s13
	s_addc_u32 s15, s15, 0
	ds_read2_b32 v[44:45], v8 offset0:40 offset1:105
	ds_read2_b32 v[46:47], v8 offset0:170 offset1:235
	ds_read2_b32 v[48:49], v9 offset0:40 offset1:105
	ds_read2_b32 v[50:51], v9 offset0:170 offset1:235
	s_waitcnt lgkmcnt(4)
	v_cvt_pk_bf16_f32 v52, v36, v37
	v_cvt_pk_bf16_f32 v53, v38, v39
	v_cvt_pk_bf16_f32 v54, v40, v41
	v_cvt_pk_bf16_f32 v55, v42, v43
	global_store_dwordx4 v17, v[52:55], s[14:15] nt
	s_add_u32 s14, s14, s13
	s_addc_u32 s15, s15, 0
	ds_read2_b32 v[36:37], v8 offset0:48 offset1:113
	ds_read2_b32 v[38:39], v8 offset0:178 offset1:243
	ds_read2_b32 v[40:41], v9 offset0:48 offset1:113
	ds_read2_b32 v[42:43], v9 offset0:178 offset1:243
	s_waitcnt lgkmcnt(4)
	v_cvt_pk_bf16_f32 v56, v44, v45
	v_cvt_pk_bf16_f32 v57, v46, v47
	v_cvt_pk_bf16_f32 v58, v48, v49
	v_cvt_pk_bf16_f32 v59, v50, v51
	global_store_dwordx4 v17, v[56:59], s[14:15] nt
	s_add_u32 s14, s14, s13
	s_addc_u32 s15, s15, 0
	ds_read2_b32 v[44:45], v8 offset0:56 offset1:121
	ds_read2_b32 v[46:47], v8 offset0:186 offset1:251
	ds_read2_b32 v[48:49], v9 offset0:56 offset1:121
	ds_read2_b32 v[50:51], v9 offset0:186 offset1:251
	s_waitcnt lgkmcnt(4)
	v_cvt_pk_bf16_f32 v52, v36, v37
	v_cvt_pk_bf16_f32 v53, v38, v39
	v_cvt_pk_bf16_f32 v54, v40, v41
	v_cvt_pk_bf16_f32 v55, v42, v43
	global_store_dwordx4 v17, v[52:55], s[14:15] nt
	s_add_u32 s14, s14, s13
	s_addc_u32 s15, s15, 0
	s_waitcnt lgkmcnt(0)
	v_cvt_pk_bf16_f32 v56, v44, v45
	v_cvt_pk_bf16_f32 v57, v46, v47
	v_cvt_pk_bf16_f32 v58, v48, v49
	v_cvt_pk_bf16_f32 v59, v50, v51
	global_store_dwordx4 v17, v[56:59], s[14:15] nt
	s_add_i32 s13, s60, 0x1403
	s_cmpk_lt_u32 s13, 0x1000
	s_cbranch_scc1 .Lcvu_dB3_c0
	s_cmpk_lt_u32 s13, 0x1400
	s_cbranch_scc1 .Lcvu_dB3_c1
	s_cmpk_lt_u32 s13, 0x2400
	s_cbranch_scc1 .Lcvu_dB3_c2
	s_add_i32 s13, s13, 0xffffdc00
	s_mov_b64 s[16:17], s[46:47]
	s_mov_b64 s[62:63], s[54:55]
	s_mov_b32 s14, 5
	s_mov_b32 s15, 19
	s_mov_b32 s19, 20
	s_mov_b32 s1, 13
	s_mov_b32 s12, 14
	s_branch .Lcvu_dB3_go

.Lcvu_dB3_go:
	s_lshr_b32 s0, s13, s14
	s_lshl_b32 s18, s0, s14
	s_sub_i32 s13, s13, s18
	s_lshl_b32 s18, s0, s15
	s_lshl_b32 s14, s13, 8
	s_add_i32 s18, s18, s14
	s_add_u32 s16, s16, s18
	s_addc_u32 s17, s17, 0
	s_lshl_b32 s18, s13, s19
	s_lshl_b32 s14, s0, 7
	s_add_i32 s18, s18, s14
	s_add_u32 s10, s62, s18
	s_addc_u32 s11, s63, 0
	s_add_i32 s18, s1, 2
	s_lshl_b32 s18, 1, s18
	v_lshlrev_b32_e32 v16, s1, v3
	v_or_b32_e32 v16, v16, v4
	global_load_dwordx4 v[136:139], v16, s[16:17] nt
	s_add_u32 s16, s16, s18
	s_addc_u32 s17, s17, 0
	global_load_dwordx4 v[140:143], v16, s[16:17] nt
	s_add_u32 s16, s16, s18
	s_addc_u32 s17, s17, 0
	global_load_dwordx4 v[144:147], v16, s[16:17] nt
	s_add_u32 s16, s16, s18
	s_addc_u32 s17, s17, 0
	global_load_dwordx4 v[148:151], v16, s[16:17] nt
	s_add_u32 s16, s16, s18
	s_addc_u32 s17, s17, 0
	global_load_dwordx4 v[152:155], v16, s[16:17] nt
	s_add_u32 s16, s16, s18
	s_addc_u32 s17, s17, 0
	global_load_dwordx4 v[156:159], v16, s[16:17] nt
	s_add_u32 s16, s16, s18
	s_addc_u32 s17, s17, 0
	global_load_dwordx4 v[160:163], v16, s[16:17] nt
	s_add_u32 s16, s16, s18
	s_addc_u32 s17, s17, 0
	global_load_dwordx4 v[164:167], v16, s[16:17] nt
	s_add_u32 s16, s16, s18
	s_addc_u32 s17, s17, 0
	global_load_dwordx4 v[168:171], v16, s[16:17] nt
	s_add_u32 s16, s16, s18
	s_addc_u32 s17, s17, 0
	global_load_dwordx4 v[172:175], v16, s[16:17] nt
	s_add_u32 s16, s16, s18
	s_addc_u32 s17, s17, 0
	global_load_dwordx4 v[176:179], v16, s[16:17] nt
	s_add_u32 s16, s16, s18
	s_addc_u32 s17, s17, 0
	global_load_dwordx4 v[180:183], v16, s[16:17] nt
	s_add_u32 s16, s16, s18
	s_addc_u32 s17, s17, 0
	global_load_dwordx4 v[184:187], v16, s[16:17] nt
	s_add_u32 s16, s16, s18
	s_addc_u32 s17, s17, 0
	global_load_dwordx4 v[188:191], v16, s[16:17] nt
	s_add_u32 s16, s16, s18
	s_addc_u32 s17, s17, 0
	global_load_dwordx4 v[192:195], v16, s[16:17] nt
	s_add_u32 s16, s16, s18
	s_addc_u32 s17, s17, 0
	global_load_dwordx4 v[196:199], v16, s[16:17] nt
	s_waitcnt vmcnt(24)
	ds_write_b32 v7, v72 offset:0
	ds_write_b32 v7, v73 offset:4
	ds_write_b32 v7, v74 offset:8
	ds_write_b32 v7, v75 offset:12
	ds_write_b32 v7, v76 offset:1040
	ds_write_b32 v7, v77 offset:1044
	ds_write_b32 v7, v78 offset:1048
	ds_write_b32 v7, v79 offset:1052
	ds_write_b32 v7, v80 offset:2080
	ds_write_b32 v7, v81 offset:2084
	ds_write_b32 v7, v82 offset:2088
	ds_write_b32 v7, v83 offset:2092
	ds_write_b32 v7, v84 offset:3120
	ds_write_b32 v7, v85 offset:3124
	ds_write_b32 v7, v86 offset:3128
	ds_write_b32 v7, v87 offset:3132
	ds_write_b32 v7, v88 offset:4160
	ds_write_b32 v7, v89 offset:4164
	ds_write_b32 v7, v90 offset:4168
	ds_write_b32 v7, v91 offset:4172
	ds_write_b32 v7, v92 offset:5200
	ds_write_b32 v7, v93 offset:5204
	ds_write_b32 v7, v94 offset:5208
	ds_write_b32 v7, v95 offset:5212
	ds_write_b32 v7, v96 offset:6240
	ds_write_b32 v7, v97 offset:6244
	ds_write_b32 v7, v98 offset:6248
	ds_write_b32 v7, v99 offset:6252
	ds_write_b32 v7, v100 offset:7280
	ds_write_b32 v7, v101 offset:7284
	ds_write_b32 v7, v102 offset:7288
	ds_write_b32 v7, v103 offset:7292
	ds_write_b32 v7, v104 offset:8320
	ds_write_b32 v7, v105 offset:8324
	ds_write_b32 v7, v106 offset:8328
	ds_write_b32 v7, v107 offset:8332
	ds_write_b32 v7, v108 offset:9360
	ds_write_b32 v7, v109 offset:9364
	ds_write_b32 v7, v110 offset:9368
	ds_write_b32 v7, v111 offset:9372
	ds_write_b32 v7, v112 offset:10400
	ds_write_b32 v7, v113 offset:10404
	ds_write_b32 v7, v114 offset:10408
	ds_write_b32 v7, v115 offset:10412
	ds_write_b32 v7, v116 offset:11440
	ds_write_b32 v7, v117 offset:11444
	ds_write_b32 v7, v118 offset:11448
	ds_write_b32 v7, v119 offset:11452
	ds_write_b32 v7, v120 offset:12480
	ds_write_b32 v7, v121 offset:12484
	ds_write_b32 v7, v122 offset:12488
	ds_write_b32 v7, v123 offset:12492
	ds_write_b32 v7, v124 offset:13520
	ds_write_b32 v7, v125 offset:13524
	ds_write_b32 v7, v126 offset:13528
	ds_write_b32 v7, v127 offset:13532
	ds_write_b32 v7, v128 offset:14560
	ds_write_b32 v7, v129 offset:14564
	ds_write_b32 v7, v130 offset:14568
	ds_write_b32 v7, v131 offset:14572
	ds_write_b32 v7, v132 offset:15600
	ds_write_b32 v7, v133 offset:15604
	ds_write_b32 v7, v134 offset:15608
	ds_write_b32 v7, v135 offset:15612
	v_lshlrev_b32_e32 v17, s8, v5
	v_or_b32_e32 v17, v17, v6
	s_lshl_b32 s13, 8, s8
	s_mov_b32 s14, s6
	s_mov_b32 s15, s7
	ds_read2_b32 v[36:37], v8 offset0:0 offset1:65
	ds_read2_b32 v[38:39], v8 offset0:130 offset1:195
	ds_read2_b32 v[40:41], v9 offset0:0 offset1:65
	ds_read2_b32 v[42:43], v9 offset0:130 offset1:195
	ds_read2_b32 v[44:45], v8 offset0:8 offset1:73
	ds_read2_b32 v[46:47], v8 offset0:138 offset1:203
	ds_read2_b32 v[48:49], v9 offset0:8 offset1:73
	ds_read2_b32 v[50:51], v9 offset0:138 offset1:203
	s_waitcnt lgkmcnt(4)
	v_cvt_pk_bf16_f32 v52, v36, v37
	v_cvt_pk_bf16_f32 v53, v38, v39
	v_cvt_pk_bf16_f32 v54, v40, v41
	v_cvt_pk_bf16_f32 v55, v42, v43
	global_store_dwordx4 v17, v[52:55], s[14:15] nt
	s_add_u32 s14, s14, s13
	s_addc_u32 s15, s15, 0
	ds_read2_b32 v[36:37], v8 offset0:16 offset1:81
	ds_read2_b32 v[38:39], v8 offset0:146 offset1:211
	ds_read2_b32 v[40:41], v9 offset0:16 offset1:81
	ds_read2_b32 v[42:43], v9 offset0:146 offset1:211
	s_waitcnt lgkmcnt(4)
	v_cvt_pk_bf16_f32 v56, v44, v45
	v_cvt_pk_bf16_f32 v57, v46, v47
	v_cvt_pk_bf16_f32 v58, v48, v49
	v_cvt_pk_bf16_f32 v59, v50, v51
	global_store_dwordx4 v17, v[56:59], s[14:15] nt
	s_add_u32 s14, s14, s13
	s_addc_u32 s15, s15, 0
	ds_read2_b32 v[44:45], v8 offset0:24 offset1:89
	ds_read2_b32 v[46:47], v8 offset0:154 offset1:219
	ds_read2_b32 v[48:49], v9 offset0:24 offset1:89
	ds_read2_b32 v[50:51], v9 offset0:154 offset1:219
	s_waitcnt lgkmcnt(4)
	v_cvt_pk_bf16_f32 v52, v36, v37
	v_cvt_pk_bf16_f32 v53, v38, v39
	v_cvt_pk_bf16_f32 v54, v40, v41
	v_cvt_pk_bf16_f32 v55, v42, v43
	global_store_dwordx4 v17, v[52:55], s[14:15] nt
	s_add_u32 s14, s14, s13
	s_addc_u32 s15, s15, 0
	ds_read2_b32 v[36:37], v8 offset0:32 offset1:97
	ds_read2_b32 v[38:39], v8 offset0:162 offset1:227
	ds_read2_b32 v[40:41], v9 offset0:32 offset1:97
	ds_read2_b32 v[42:43], v9 offset0:162 offset1:227
	s_waitcnt lgkmcnt(4)
	v_cvt_pk_bf16_f32 v56, v44, v45
	v_cvt_pk_bf16_f32 v57, v46, v47
	v_cvt_pk_bf16_f32 v58, v48, v49
	v_cvt_pk_bf16_f32 v59, v50, v51
	global_store_dwordx4 v17, v[56:59], s[14:15] nt
	s_add_u32 s14, s14, s13
	s_addc_u32 s15, s15, 0
	ds_read2_b32 v[44:45], v8 offset0:40 offset1:105
	ds_read2_b32 v[46:47], v8 offset0:170 offset1:235
	ds_read2_b32 v[48:49], v9 offset0:40 offset1:105
	ds_read2_b32 v[50:51], v9 offset0:170 offset1:235
	s_waitcnt lgkmcnt(4)
	v_cvt_pk_bf16_f32 v52, v36, v37
	v_cvt_pk_bf16_f32 v53, v38, v39
	v_cvt_pk_bf16_f32 v54, v40, v41
	v_cvt_pk_bf16_f32 v55, v42, v43
	global_store_dwordx4 v17, v[52:55], s[14:15] nt
	s_add_u32 s14, s14, s13
	s_addc_u32 s15, s15, 0
	ds_read2_b32 v[36:37], v8 offset0:48 offset1:113
	ds_read2_b32 v[38:39], v8 offset0:178 offset1:243
	ds_read2_b32 v[40:41], v9 offset0:48 offset1:113
	ds_read2_b32 v[42:43], v9 offset0:178 offset1:243
	s_waitcnt lgkmcnt(4)
	v_cvt_pk_bf16_f32 v56, v44, v45
	v_cvt_pk_bf16_f32 v57, v46, v47
	v_cvt_pk_bf16_f32 v58, v48, v49
	v_cvt_pk_bf16_f32 v59, v50, v51
	global_store_dwordx4 v17, v[56:59], s[14:15] nt
	s_add_u32 s14, s14, s13
	s_addc_u32 s15, s15, 0
	ds_read2_b32 v[44:45], v8 offset0:56 offset1:121
	ds_read2_b32 v[46:47], v8 offset0:186 offset1:251
	ds_read2_b32 v[48:49], v9 offset0:56 offset1:121
	ds_read2_b32 v[50:51], v9 offset0:186 offset1:251
	s_waitcnt lgkmcnt(4)
	v_cvt_pk_bf16_f32 v52, v36, v37
	v_cvt_pk_bf16_f32 v53, v38, v39
	v_cvt_pk_bf16_f32 v54, v40, v41
	v_cvt_pk_bf16_f32 v55, v42, v43
	global_store_dwordx4 v17, v[52:55], s[14:15] nt
	s_add_u32 s14, s14, s13
	s_addc_u32 s15, s15, 0
	s_waitcnt lgkmcnt(0)
	v_cvt_pk_bf16_f32 v56, v44, v45
	v_cvt_pk_bf16_f32 v57, v46, v47
	v_cvt_pk_bf16_f32 v58, v48, v49
	v_cvt_pk_bf16_f32 v59, v50, v51
	global_store_dwordx4 v17, v[56:59], s[14:15] nt
	v_readfirstlane_b32 s60, v19
	s_nop 3
	s_cmpk_lt_u32 s60, 0x2000
	s_cbranch_scc1 .Lcvu_grab
	s_waitcnt vmcnt(8)
	ds_write_b32 v7, v136 offset:0
	ds_write_b32 v7, v137 offset:4
	ds_write_b32 v7, v138 offset:8
	ds_write_b32 v7, v139 offset:12
	ds_write_b32 v7, v140 offset:1040
	ds_write_b32 v7, v141 offset:1044
	ds_write_b32 v7, v142 offset:1048
	ds_write_b32 v7, v143 offset:1052
	ds_write_b32 v7, v144 offset:2080
	ds_write_b32 v7, v145 offset:2084
	ds_write_b32 v7, v146 offset:2088
	ds_write_b32 v7, v147 offset:2092
	ds_write_b32 v7, v148 offset:3120
	ds_write_b32 v7, v149 offset:3124
	ds_write_b32 v7, v150 offset:3128
	ds_write_b32 v7, v151 offset:3132
	ds_write_b32 v7, v152 offset:4160
	ds_write_b32 v7, v153 offset:4164
	ds_write_b32 v7, v154 offset:4168
	ds_write_b32 v7, v155 offset:4172
	ds_write_b32 v7, v156 offset:5200
	ds_write_b32 v7, v157 offset:5204
	ds_write_b32 v7, v158 offset:5208
	ds_write_b32 v7, v159 offset:5212
	ds_write_b32 v7, v160 offset:6240
	ds_write_b32 v7, v161 offset:6244
	ds_write_b32 v7, v162 offset:6248
	ds_write_b32 v7, v163 offset:6252
	ds_write_b32 v7, v164 offset:7280
	ds_write_b32 v7, v165 offset:7284
	ds_write_b32 v7, v166 offset:7288
	ds_write_b32 v7, v167 offset:7292
	ds_write_b32 v7, v168 offset:8320
	ds_write_b32 v7, v169 offset:8324
	ds_write_b32 v7, v170 offset:8328
	ds_write_b32 v7, v171 offset:8332
	ds_write_b32 v7, v172 offset:9360
	ds_write_b32 v7, v173 offset:9364
	ds_write_b32 v7, v174 offset:9368
	ds_write_b32 v7, v175 offset:9372
	ds_write_b32 v7, v176 offset:10400
	ds_write_b32 v7, v177 offset:10404
	ds_write_b32 v7, v178 offset:10408
	ds_write_b32 v7, v179 offset:10412
	ds_write_b32 v7, v180 offset:11440
	ds_write_b32 v7, v181 offset:11444
	ds_write_b32 v7, v182 offset:11448
	ds_write_b32 v7, v183 offset:11452
	ds_write_b32 v7, v184 offset:12480
	ds_write_b32 v7, v185 offset:12484
	ds_write_b32 v7, v186 offset:12488
	ds_write_b32 v7, v187 offset:12492
	ds_write_b32 v7, v188 offset:13520
	ds_write_b32 v7, v189 offset:13524
	ds_write_b32 v7, v190 offset:13528
	ds_write_b32 v7, v191 offset:13532
	ds_write_b32 v7, v192 offset:14560
	ds_write_b32 v7, v193 offset:14564
	ds_write_b32 v7, v194 offset:14568
	ds_write_b32 v7, v195 offset:14572
	ds_write_b32 v7, v196 offset:15600
	ds_write_b32 v7, v197 offset:15604
	ds_write_b32 v7, v198 offset:15608
	ds_write_b32 v7, v199 offset:15612
	v_lshlrev_b32_e32 v17, s12, v5
	v_or_b32_e32 v17, v17, v6
	s_lshl_b32 s13, 8, s12
	s_mov_b32 s14, s10
	s_mov_b32 s15, s11
	ds_read2_b32 v[36:37], v8 offset0:0 offset1:65
	ds_read2_b32 v[38:39], v8 offset0:130 offset1:195
	ds_read2_b32 v[40:41], v9 offset0:0 offset1:65
	ds_read2_b32 v[42:43], v9 offset0:130 offset1:195
	ds_read2_b32 v[44:45], v8 offset0:8 offset1:73
	ds_read2_b32 v[46:47], v8 offset0:138 offset1:203
	ds_read2_b32 v[48:49], v9 offset0:8 offset1:73
	ds_read2_b32 v[50:51], v9 offset0:138 offset1:203
	s_waitcnt lgkmcnt(4)
	v_cvt_pk_bf16_f32 v52, v36, v37
	v_cvt_pk_bf16_f32 v53, v38, v39
	v_cvt_pk_bf16_f32 v54, v40, v41
	v_cvt_pk_bf16_f32 v55, v42, v43
	global_store_dwordx4 v17, v[52:55], s[14:15] nt
	s_add_u32 s14, s14, s13
	s_addc_u32 s15, s15, 0
	ds_read2_b32 v[36:37], v8 offset0:16 offset1:81
	ds_read2_b32 v[38:39], v8 offset0:146 offset1:211
	ds_read2_b32 v[40:41], v9 offset0:16 offset1:81
	ds_read2_b32 v[42:43], v9 offset0:146 offset1:211
	s_waitcnt lgkmcnt(4)
	v_cvt_pk_bf16_f32 v56, v44, v45
	v_cvt_pk_bf16_f32 v57, v46, v47
	v_cvt_pk_bf16_f32 v58, v48, v49
	v_cvt_pk_bf16_f32 v59, v50, v51
	global_store_dwordx4 v17, v[56:59], s[14:15] nt
	s_add_u32 s14, s14, s13
	s_addc_u32 s15, s15, 0
	ds_read2_b32 v[44:45], v8 offset0:24 offset1:89
	ds_read2_b32 v[46:47], v8 offset0:154 offset1:219
	ds_read2_b32 v[48:49], v9 offset0:24 offset1:89
	ds_read2_b32 v[50:51], v9 offset0:154 offset1:219
	s_waitcnt lgkmcnt(4)
	v_cvt_pk_bf16_f32 v52, v36, v37
	v_cvt_pk_bf16_f32 v53, v38, v39
	v_cvt_pk_bf16_f32 v54, v40, v41
	v_cvt_pk_bf16_f32 v55, v42, v43
	global_store_dwordx4 v17, v[52:55], s[14:15] nt
	s_add_u32 s14, s14, s13
	s_addc_u32 s15, s15, 0
	ds_read2_b32 v[36:37], v8 offset0:32 offset1:97
	ds_read2_b32 v[38:39], v8 offset0:162 offset1:227
	ds_read2_b32 v[40:41], v9 offset0:32 offset1:97
	ds_read2_b32 v[42:43], v9 offset0:162 offset1:227
	s_waitcnt lgkmcnt(4)
	v_cvt_pk_bf16_f32 v56, v44, v45
	v_cvt_pk_bf16_f32 v57, v46, v47
	v_cvt_pk_bf16_f32 v58, v48, v49
	v_cvt_pk_bf16_f32 v59, v50, v51
	global_store_dwordx4 v17, v[56:59], s[14:15] nt
	s_add_u32 s14, s14, s13
	s_addc_u32 s15, s15, 0
	ds_read2_b32 v[44:45], v8 offset0:40 offset1:105
	ds_read2_b32 v[46:47], v8 offset0:170 offset1:235
	ds_read2_b32 v[48:49], v9 offset0:40 offset1:105
	ds_read2_b32 v[50:51], v9 offset0:170 offset1:235
	s_waitcnt lgkmcnt(4)
	v_cvt_pk_bf16_f32 v52, v36, v37
	v_cvt_pk_bf16_f32 v53, v38, v39
	v_cvt_pk_bf16_f32 v54, v40, v41
	v_cvt_pk_bf16_f32 v55, v42, v43
	global_store_dwordx4 v17, v[52:55], s[14:15] nt
	s_add_u32 s14, s14, s13
	s_addc_u32 s15, s15, 0
	ds_read2_b32 v[36:37], v8 offset0:48 offset1:113
	ds_read2_b32 v[38:39], v8 offset0:178 offset1:243
	ds_read2_b32 v[40:41], v9 offset0:48 offset1:113
	ds_read2_b32 v[42:43], v9 offset0:178 offset1:243
	s_waitcnt lgkmcnt(4)
	v_cvt_pk_bf16_f32 v56, v44, v45
	v_cvt_pk_bf16_f32 v57, v46, v47
	v_cvt_pk_bf16_f32 v58, v48, v49
	v_cvt_pk_bf16_f32 v59, v50, v51
	global_store_dwordx4 v17, v[56:59], s[14:15] nt
	s_add_u32 s14, s14, s13
	s_addc_u32 s15, s15, 0
	ds_read2_b32 v[44:45], v8 offset0:56 offset1:121
	ds_read2_b32 v[46:47], v8 offset0:186 offset1:251
	ds_read2_b32 v[48:49], v9 offset0:56 offset1:121
	ds_read2_b32 v[50:51], v9 offset0:186 offset1:251
	s_waitcnt lgkmcnt(4)
	v_cvt_pk_bf16_f32 v52, v36, v37
	v_cvt_pk_bf16_f32 v53, v38, v39
	v_cvt_pk_bf16_f32 v54, v40, v41
	v_cvt_pk_bf16_f32 v55, v42, v43
	global_store_dwordx4 v17, v[52:55], s[14:15] nt
	s_add_u32 s14, s14, s13
	s_addc_u32 s15, s15, 0
	s_waitcnt lgkmcnt(0)
	v_cvt_pk_bf16_f32 v56, v44, v45
	v_cvt_pk_bf16_f32 v57, v46, v47
	v_cvt_pk_bf16_f32 v58, v48, v49
	v_cvt_pk_bf16_f32 v59, v50, v51
	global_store_dwordx4 v17, v[56:59], s[14:15] nt
	s_branch .Lcvu_done
.Lcvu_first:
	s_mov_b32 s61, 0
	s_add_i32 s13, s60, 0x1401
	s_cmpk_lt_u32 s13, 0x1000
	s_cbranch_scc1 .Lcvu_dB4_c0
	s_cmpk_lt_u32 s13, 0x1400
	s_cbranch_scc1 .Lcvu_dB4_c1
	s_cmpk_lt_u32 s13, 0x2400
	s_cbranch_scc1 .Lcvu_dB4_c2
	s_add_i32 s13, s13, 0xffffdc00
	s_mov_b64 s[16:17], s[46:47]
	s_mov_b64 s[62:63], s[54:55]
	s_mov_b32 s14, 5
	s_mov_b32 s15, 19
	s_mov_b32 s19, 20
	s_mov_b32 s1, 13
	s_mov_b32 s12, 14
	s_branch .Lcvu_dB4_go

.Lcvu_done:
	s_waitcnt vmcnt(0) lgkmcnt(0)
	s_branch .LBB0_1452
	v_mov_b32_e32 v2, v0
	v_readlane_b32 s0, v253, 49
	v_readlane_b32 s1, v253, 50
	v_and_b32_e32 v68, 63, v2
	s_add_i32 s4, s0, 1
	v_readfirstlane_b32 s12, v2
	v_mov_b32_e32 v2, 0
	v_cmp_eq_u32_e64 s[40:41], 0, v68
	s_and_saveexec_b64 s[0:1], s[40:41]
	s_cbranch_execz .LBB0_1400
	s_mov_b64 s[8:9], exec
	v_mbcnt_lo_u32_b32 v2, s8, 0
	v_mbcnt_hi_u32_b32 v2, s9, v2
	v_cmp_eq_u32_e32 vcc, 0, v2
	s_and_saveexec_b64 s[6:7], vcc
	s_cbranch_execz .LBB0_1399
	s_lshl_b32 s10, s4, 6
	s_mov_b32 s11, s5
	s_lshl_b64 s[10:11], s[10:11], 2
	s_add_u32 s10, s26, s10
	s_addc_u32 s11, s27, s11
	s_bcnt1_i32_b64 s8, s[8:9]
	s_lshl_b32 s8, s8, 3
	v_mov_b32_e32 v3, s8
	global_atomic_add v3, v35, v3, s[10:11] offset:576 sc0
